# peeled first K-loop iteration of the GEMM unit loops (C=0 on first MFMA per accumulator), accumulator zeroing removed
# speedup vs baseline: 1.0086x; 1.0086x over previous
.LBB0_174:
	v_lshrrev_b32_e32 v18, 1, v15
	s_add_u32 s46, s9, 0x19c00000
	v_and_b32_e32 v18, 24, v18
	s_addc_u32 s47, s10, 0
	v_and_b32_e32 v16, 15, v15
	s_lshl_b32 s17, s1, 6
	v_lshlrev_b32_e32 v19, 1, v18
	v_lshlrev_b32_e32 v15, 2, v15
	s_and_b32 s6, s0, 3
	v_or_b32_e32 v17, s17, v16
	v_lshl_or_b32 v16, v16, 6, v19
	s_lshl_b32 s0, s1, 13
	v_and_b32_e32 v15, 32, v15
	s_add_i32 m0, s73, 0x18000
	v_lshl_add_u64 v[8:9], v[8:9], 0, s[24:25]
	v_bitop3_b32 v19, v16, s0, v15 bitop3:0xde
	s_lshl_b32 s0, s6, 12
	s_waitcnt vmcnt(4)
	s_barrier
	global_load_lds_dwordx4 v[8:9], off
	v_lshl_add_u64 v[6:7], v[6:7], 0, s[24:25]
	s_add_i32 m0, s73, 0x1a000
	s_add_i32 s18, s73, 0x8000
	s_add_i32 s19, s73, 0xa000
	v_bitop3_b32 v155, v16, s0, v15 bitop3:0xde
	global_load_lds_dwordx4 v[6:7], off
	v_lshl_add_u64 v[4:5], v[4:5], 0, s[24:25]
	s_mov_b32 m0, s18
	s_add_u32 s0, s62, 0x40080
	global_load_lds_dwordx4 v[4:5], off
	v_lshl_add_u64 v[2:3], v[2:3], 0, s[24:25]
	s_mov_b32 m0, s19
	s_addc_u32 s1, s63, 0
	global_load_lds_dwordx4 v[2:3], off
	s_add_i32 m0, s73, 0x1c000
	v_lshl_add_u64 v[2:3], s[0:1], 0, v[146:147]
	global_load_lds_dwordx4 v[2:3], off
	v_lshl_add_u64 v[2:3], s[0:1], 0, v[148:149]
	s_add_i32 m0, s73, 0x1e000
	v_add_u32_e32 v245, 0x80, v17
	global_load_lds_dwordx4 v[2:3], off
	v_lshlrev_b32_e32 v2, 8, v17
	v_and_b32_e32 v244, 0xcf00, v2
	v_lshlrev_b32_e32 v2, 8, v245
	v_add_u32_e32 v247, 0x90, v17
	v_and_b32_e32 v246, 0xcf00, v2
	v_lshlrev_b32_e32 v2, 8, v247
	v_add_u32_e32 v249, 0xa0, v17
	v_and_b32_e32 v248, 0xdf00, v2
	v_lshlrev_b32_e32 v2, 8, v249
	v_add_u32_e32 v251, 0xb0, v17
	v_and_b32_e32 v250, 0xef00, v2
	v_lshlrev_b32_e32 v2, 8, v251
	v_and_b32_e32 v252, 0xff00, v2
	v_lshlrev_b32_e32 v2, 14, v0
	v_and_b32_e32 v2, 0xffff8000, v2
	v_lshl_add_u32 v2, v10, 11, v2
	v_and_b32_e32 v0, 1, v0
	v_lshl_or_b32 v0, v0, 6, v2
	v_lshl_add_u32 v150, v11, 1, v0
	v_lshlrev_b32_e32 v0, 14, v12
	v_and_b32_e32 v0, 0xffff8000, v0
	s_waitcnt vmcnt(6)
	v_lshl_add_u32 v0, v13, 11, v0
	v_and_b32_e32 v2, 1, v12
	s_add_i32 s0, 0, 0x20000
	v_lshl_or_b32 v0, v2, 6, v0
	v_lshl_add_u32 v179, v18, 2, s0
	s_ashr_i32 s20, s48, 31
	v_lshl_or_b32 v253, s6, 6, v18
	v_mov_b32_e32 v151, v1
	v_lshl_add_u32 v152, v14, 1, v0
	v_mov_b32_e32 v153, v1
	s_mov_b32 s21, 0
	v_add_u32_e32 v231, 0, v19
	s_barrier
	s_branch .LBB0_176
	s_nop 0
	s_nop 0
	s_nop 0
	s_nop 0
.LBB0_175:
	s_and_b64 vcc, exec, s[36:37]
	s_mov_b32 s72, s68
	s_mov_b32 s38, s0
	s_mov_b64 s[62:63], s[88:89]
	s_mov_b64 s[2:3], s[84:85]
	global_store_dwordx4 v[156:157], v[130:133], off offset:64 nt
	s_cmpk_gt_u32 s8, 0xff
	s_cbranch_scc0 .Lepi1_proj
	s_barrier

.LBB0_178:
	s_ashr_i32 s1, s0, 31
	v_mov_b64_e32 v[2:3], 0x1300
	s_lshl_b64 s[22:23], s[0:1], 19
	v_cmp_lt_i64_e32 vcc, s[84:85], v[2:3]
	s_add_u32 s84, s12, s22
	s_addc_u32 s85, s13, s23
	s_and_b64 s[22:23], vcc, exec
	s_cselect_b32 s1, s85, s3
	s_cselect_b32 s22, s84, s2
	s_ashr_i32 s69, s68, 31
	s_lshl_b64 s[88:89], s[68:69], 19
	s_add_u32 s88, s9, s88
	s_addc_u32 s89, s10, s89
	s_and_b64 s[90:91], vcc, exec
	s_cselect_b32 s23, s89, s63
	s_cselect_b32 s39, s88, s62
	s_add_u32 s2, s2, 0x40080
	s_addc_u32 s3, s3, 0
	s_add_u32 s69, s62, 0x100
	s_addc_u32 vcc_lo, s63, 0
	s_mov_b32 vcc_hi, -2
	s_add_u32 s6, s2, 0xfffc0080
	s_addc_u32 s7, s3, -1
	s_add_i32 s33, 0, 0x10000
	v_add_u32_e32 v0, s33, v155
	ds_read_b128 v[130:133], v0
	ds_read_b128 v[134:137], v0 offset:1024
	ds_read_b128 v[138:141], v0 offset:2048
	ds_read_b128 v[142:145], v0 offset:3072
	s_cmp_eq_u32 vcc_hi, 12
	s_cselect_b32 s91, s1, s7
	s_cselect_b32 s90, s22, s6
	s_cselect_b32 s63, s23, vcc_lo
	s_cselect_b32 s62, s39, s69
	v_lshl_add_u64 v[176:177], s[2:3], 0, v[150:151]
	s_add_i32 m0, s73, 0xc000
	ds_read_b128 v[156:159], v231
	ds_read_b128 v[160:163], v231 offset:1024
	ds_read_b128 v[164:167], v231 offset:2048
	ds_read_b128 v[168:171], v231 offset:3072
	ds_read_b128 v[172:175], v231 offset:4096
	ds_read_b128 v[184:187], v231 offset:5120
	ds_read_b128 v[188:191], v231 offset:6144
	ds_read_b128 v[192:195], v231 offset:7168
	global_load_lds_dwordx4 v[176:177], off
	v_lshl_add_u64 v[176:177], s[2:3], 0, v[152:153]
	s_add_i32 m0, s73, 0xe000
	s_nop 0
	global_load_lds_dwordx4 v[176:177], off
	s_waitcnt lgkmcnt(8)
	s_barrier
	s_waitcnt lgkmcnt(0)
	s_waitcnt lgkmcnt(0)
	v_mfma_f32_16x16x32_bf16 v[126:129], v[130:133], v[156:159], 0
	v_mfma_f32_16x16x32_bf16 v[122:125], v[138:141], v[156:159], 0
	v_mfma_f32_16x16x32_bf16 v[110:113], v[130:133], v[164:167], 0
	v_mfma_f32_16x16x32_bf16 v[106:109], v[138:141], v[164:167], 0
	v_mfma_f32_16x16x32_bf16 v[94:97], v[130:133], v[172:175], 0
	v_mfma_f32_16x16x32_bf16 v[90:93], v[138:141], v[172:175], 0
	v_mfma_f32_16x16x32_bf16 v[78:81], v[130:133], v[188:191], 0
	v_mfma_f32_16x16x32_bf16 v[74:77], v[138:141], v[188:191], 0
	v_mfma_f32_16x16x32_bf16 v[126:129], v[134:137], v[160:163], v[126:129]
	v_mfma_f32_16x16x32_bf16 v[122:125], v[142:145], v[160:163], v[122:125]
	v_mfma_f32_16x16x32_bf16 v[110:113], v[134:137], v[168:171], v[110:113]
	v_mfma_f32_16x16x32_bf16 v[106:109], v[142:145], v[168:171], v[106:109]
	v_mfma_f32_16x16x32_bf16 v[94:97], v[134:137], v[184:187], v[94:97]
	v_mfma_f32_16x16x32_bf16 v[90:93], v[142:145], v[184:187], v[90:93]
	v_mfma_f32_16x16x32_bf16 v[78:81], v[134:137], v[192:195], v[78:81]
	v_mfma_f32_16x16x32_bf16 v[74:77], v[142:145], v[192:195], v[74:77]
	s_barrier
	s_add_i32 s94, 0, 0x14000
	s_add_i32 s6, s33, s11
	v_add_u32_e32 v0, s94, v155
	v_lshl_add_u64 v[176:177], s[62:63], 0, v[146:147]
	s_mov_b32 m0, s6
	ds_read_b128 v[196:199], v0
	ds_read_b128 v[200:203], v0 offset:1024
	ds_read_b128 v[204:207], v0 offset:2048
	ds_read_b128 v[208:211], v0 offset:3072
	global_load_lds_dwordx4 v[176:177], off
	v_lshl_add_u64 v[180:181], s[62:63], 0, v[148:149]
	s_add_i32 m0, s6, 0x2000
	s_nop 0
	global_load_lds_dwordx4 v[180:181], off
	s_barrier
	s_waitcnt lgkmcnt(0)
	s_waitcnt lgkmcnt(0)
	v_mfma_f32_16x16x32_bf16 v[118:121], v[196:199], v[156:159], 0
	v_mfma_f32_16x16x32_bf16 v[114:117], v[204:207], v[156:159], 0
	v_mfma_f32_16x16x32_bf16 v[102:105], v[196:199], v[164:167], 0
	v_mfma_f32_16x16x32_bf16 v[98:101], v[204:207], v[164:167], 0
	v_mfma_f32_16x16x32_bf16 v[86:89], v[196:199], v[172:175], 0
	v_mfma_f32_16x16x32_bf16 v[82:85], v[204:207], v[172:175], 0
	v_mfma_f32_16x16x32_bf16 v[70:73], v[196:199], v[188:191], 0
	v_mfma_f32_16x16x32_bf16 v[66:69], v[204:207], v[188:191], 0
	v_mfma_f32_16x16x32_bf16 v[118:121], v[200:203], v[160:163], v[118:121]
	v_mfma_f32_16x16x32_bf16 v[114:117], v[208:211], v[160:163], v[114:117]
	v_mfma_f32_16x16x32_bf16 v[102:105], v[200:203], v[168:171], v[102:105]
	v_mfma_f32_16x16x32_bf16 v[98:101], v[208:211], v[168:171], v[98:101]
	v_mfma_f32_16x16x32_bf16 v[86:89], v[200:203], v[184:187], v[86:89]
	v_mfma_f32_16x16x32_bf16 v[82:85], v[208:211], v[184:187], v[82:85]
	v_mfma_f32_16x16x32_bf16 v[70:73], v[200:203], v[192:195], v[70:73]
	v_mfma_f32_16x16x32_bf16 v[66:69], v[208:211], v[192:195], v[66:69]
	s_mov_b32 m0, s73
	v_lshl_add_u64 v[212:213], s[90:91], 0, v[146:147]
	s_barrier
	ds_read_b128 v[156:159], v231 offset:16384
	ds_read_b128 v[160:163], v231 offset:17408
	ds_read_b128 v[164:167], v231 offset:18432
	ds_read_b128 v[168:171], v231 offset:19456
	ds_read_b128 v[172:175], v231 offset:20480
	ds_read_b128 v[184:187], v231 offset:21504
	ds_read_b128 v[188:191], v231 offset:22528
	ds_read_b128 v[192:195], v231 offset:23552
	global_load_lds_dwordx4 v[212:213], off
	v_lshl_add_u64 v[214:215], s[90:91], 0, v[148:149]
	s_mov_b32 m0, s14
	s_nop 0
	global_load_lds_dwordx4 v[214:215], off
	s_barrier
	s_waitcnt lgkmcnt(0)
	s_waitcnt lgkmcnt(0)
	v_mfma_f32_16x16x32_bf16 v[62:65], v[130:133], v[156:159], 0
	v_mfma_f32_16x16x32_bf16 v[58:61], v[138:141], v[156:159], 0
	v_mfma_f32_16x16x32_bf16 v[46:49], v[130:133], v[164:167], 0
	v_mfma_f32_16x16x32_bf16 v[42:45], v[138:141], v[164:167], 0
	v_mfma_f32_16x16x32_bf16 v[30:33], v[130:133], v[172:175], 0
	v_mfma_f32_16x16x32_bf16 v[26:29], v[138:141], v[172:175], 0
	v_mfma_f32_16x16x32_bf16 v[14:17], v[130:133], v[188:191], 0
	v_mfma_f32_16x16x32_bf16 v[10:13], v[138:141], v[188:191], 0
	v_mfma_f32_16x16x32_bf16 v[62:65], v[134:137], v[160:163], v[62:65]
	v_mfma_f32_16x16x32_bf16 v[58:61], v[142:145], v[160:163], v[58:61]
	v_mfma_f32_16x16x32_bf16 v[46:49], v[134:137], v[168:171], v[46:49]
	v_mfma_f32_16x16x32_bf16 v[42:45], v[142:145], v[168:171], v[42:45]
	v_mfma_f32_16x16x32_bf16 v[30:33], v[134:137], v[184:187], v[30:33]
	v_mfma_f32_16x16x32_bf16 v[26:29], v[142:145], v[184:187], v[26:29]
	v_mfma_f32_16x16x32_bf16 v[14:17], v[134:137], v[192:195], v[14:17]
	v_mfma_f32_16x16x32_bf16 v[10:13], v[142:145], v[192:195], v[10:13]
	s_barrier
	s_add_u32 s6, s62, 0x40000
	s_addc_u32 s7, s63, 0
	s_add_i32 s33, s94, s11
	v_lshl_add_u64 v[130:131], s[6:7], 0, v[146:147]
	s_mov_b32 m0, s33
	s_nop 0
	global_load_lds_dwordx4 v[130:131], off
	v_lshl_add_u64 v[130:131], s[6:7], 0, v[148:149]
	s_add_i32 m0, s33, 0x2000
	s_nop 0
	global_load_lds_dwordx4 v[130:131], off
	s_waitcnt vmcnt(6)
	s_barrier
	v_mfma_f32_16x16x32_bf16 v[54:57], v[196:199], v[156:159], 0
	v_mfma_f32_16x16x32_bf16 v[50:53], v[204:207], v[156:159], 0
	v_mfma_f32_16x16x32_bf16 v[38:41], v[196:199], v[164:167], 0
	v_mfma_f32_16x16x32_bf16 v[34:37], v[204:207], v[164:167], 0
	v_mfma_f32_16x16x32_bf16 v[22:25], v[196:199], v[172:175], 0
	v_mfma_f32_16x16x32_bf16 v[18:21], v[204:207], v[172:175], 0
	v_mfma_f32_16x16x32_bf16 v[6:9], v[196:199], v[188:191], 0
	v_mfma_f32_16x16x32_bf16 v[2:5], v[204:207], v[188:191], 0
	v_mfma_f32_16x16x32_bf16 v[54:57], v[200:203], v[160:163], v[54:57]
	v_mfma_f32_16x16x32_bf16 v[50:53], v[208:211], v[160:163], v[50:53]
	v_mfma_f32_16x16x32_bf16 v[38:41], v[200:203], v[168:171], v[38:41]
	v_mfma_f32_16x16x32_bf16 v[34:37], v[208:211], v[168:171], v[34:37]
	v_mfma_f32_16x16x32_bf16 v[22:25], v[200:203], v[184:187], v[22:25]
	v_mfma_f32_16x16x32_bf16 v[18:21], v[208:211], v[184:187], v[18:21]
	v_mfma_f32_16x16x32_bf16 v[6:9], v[200:203], v[192:195], v[6:9]
	v_mfma_f32_16x16x32_bf16 v[2:5], v[208:211], v[192:195], v[2:5]
	s_add_i32 s33, 0, 0x18000
	v_add_u32_e32 v0, s33, v155
	s_barrier
	ds_read_b128 v[130:133], v0
	ds_read_b128 v[134:137], v0 offset:1024
	ds_read_b128 v[138:141], v0 offset:2048
	ds_read_b128 v[142:145], v0 offset:3072
	s_add_u32 s6, s90, 0x40000
	s_addc_u32 s7, s91, 0
	s_mov_b32 m0, s15
	v_lshl_add_u64 v[196:197], s[6:7], 0, v[146:147]
	ds_read_b128 v[156:159], v231 offset:32768
	ds_read_b128 v[160:163], v231 offset:33792
	ds_read_b128 v[164:167], v231 offset:34816
	ds_read_b128 v[168:171], v231 offset:35840
	ds_read_b128 v[172:175], v231 offset:36864
	ds_read_b128 v[184:187], v231 offset:37888
	ds_read_b128 v[188:191], v231 offset:38912
	ds_read_b128 v[192:195], v231 offset:39936
	global_load_lds_dwordx4 v[196:197], off
	v_lshl_add_u64 v[196:197], s[6:7], 0, v[148:149]
	s_mov_b32 m0, s16
	s_nop 0
	global_load_lds_dwordx4 v[196:197], off
	s_waitcnt lgkmcnt(8)
	s_barrier
	s_waitcnt lgkmcnt(0)
	s_waitcnt lgkmcnt(0)
	v_mfma_f32_16x16x32_bf16 v[126:129], v[130:133], v[156:159], v[126:129]
	v_mfma_f32_16x16x32_bf16 v[122:125], v[138:141], v[156:159], v[122:125]
	v_mfma_f32_16x16x32_bf16 v[110:113], v[130:133], v[164:167], v[110:113]
	v_mfma_f32_16x16x32_bf16 v[106:109], v[138:141], v[164:167], v[106:109]
	v_mfma_f32_16x16x32_bf16 v[94:97], v[130:133], v[172:175], v[94:97]
	v_mfma_f32_16x16x32_bf16 v[90:93], v[138:141], v[172:175], v[90:93]
	v_mfma_f32_16x16x32_bf16 v[78:81], v[130:133], v[188:191], v[78:81]
	v_mfma_f32_16x16x32_bf16 v[74:77], v[138:141], v[188:191], v[74:77]
	v_mfma_f32_16x16x32_bf16 v[126:129], v[134:137], v[160:163], v[126:129]
	v_mfma_f32_16x16x32_bf16 v[122:125], v[142:145], v[160:163], v[122:125]
	v_mfma_f32_16x16x32_bf16 v[110:113], v[134:137], v[168:171], v[110:113]
	v_mfma_f32_16x16x32_bf16 v[106:109], v[142:145], v[168:171], v[106:109]
	v_mfma_f32_16x16x32_bf16 v[94:97], v[134:137], v[184:187], v[94:97]
	v_mfma_f32_16x16x32_bf16 v[90:93], v[142:145], v[184:187], v[90:93]
	v_mfma_f32_16x16x32_bf16 v[78:81], v[134:137], v[192:195], v[78:81]
	v_mfma_f32_16x16x32_bf16 v[74:77], v[142:145], v[192:195], v[74:77]
	s_barrier
	s_add_i32 s90, 0, 0x1c000
	s_add_i32 s6, s33, s11
	v_add_u32_e32 v0, s90, v155
	v_lshl_add_u64 v[176:177], v[176:177], 0, s[24:25]
	s_mov_b32 m0, s6
	ds_read_b128 v[196:199], v0
	ds_read_b128 v[200:203], v0 offset:1024
	ds_read_b128 v[204:207], v0 offset:2048
	ds_read_b128 v[208:211], v0 offset:3072
	global_load_lds_dwordx4 v[176:177], off
	v_lshl_add_u64 v[176:177], v[180:181], 0, s[24:25]
	s_add_i32 m0, s6, 0x2000
	s_nop 0
	global_load_lds_dwordx4 v[176:177], off
	s_barrier
	s_waitcnt lgkmcnt(0)
	s_waitcnt lgkmcnt(0)
	v_mfma_f32_16x16x32_bf16 v[118:121], v[196:199], v[156:159], v[118:121]
	v_mfma_f32_16x16x32_bf16 v[114:117], v[204:207], v[156:159], v[114:117]
	v_mfma_f32_16x16x32_bf16 v[102:105], v[196:199], v[164:167], v[102:105]
	v_mfma_f32_16x16x32_bf16 v[98:101], v[204:207], v[164:167], v[98:101]
	v_mfma_f32_16x16x32_bf16 v[86:89], v[196:199], v[172:175], v[86:89]
	v_mfma_f32_16x16x32_bf16 v[82:85], v[204:207], v[172:175], v[82:85]
	v_mfma_f32_16x16x32_bf16 v[70:73], v[196:199], v[188:191], v[70:73]
	v_mfma_f32_16x16x32_bf16 v[66:69], v[204:207], v[188:191], v[66:69]
	v_mfma_f32_16x16x32_bf16 v[118:121], v[200:203], v[160:163], v[118:121]
	v_mfma_f32_16x16x32_bf16 v[114:117], v[208:211], v[160:163], v[114:117]
	v_mfma_f32_16x16x32_bf16 v[102:105], v[200:203], v[168:171], v[102:105]
	v_mfma_f32_16x16x32_bf16 v[98:101], v[208:211], v[168:171], v[98:101]
	v_mfma_f32_16x16x32_bf16 v[86:89], v[200:203], v[184:187], v[86:89]
	v_mfma_f32_16x16x32_bf16 v[82:85], v[208:211], v[184:187], v[82:85]
	v_mfma_f32_16x16x32_bf16 v[70:73], v[200:203], v[192:195], v[70:73]
	v_mfma_f32_16x16x32_bf16 v[66:69], v[208:211], v[192:195], v[66:69]
	s_mov_b32 m0, s18
	v_lshl_add_u64 v[176:177], v[212:213], 0, s[24:25]
	s_barrier
	ds_read_b128 v[156:159], v231 offset:49152
	ds_read_b128 v[160:163], v231 offset:50176
	ds_read_b128 v[164:167], v231 offset:51200
	ds_read_b128 v[168:171], v231 offset:52224
	ds_read_b128 v[172:175], v231 offset:53248
	ds_read_b128 v[184:187], v231 offset:54272
	ds_read_b128 v[188:191], v231 offset:55296
	ds_read_b128 v[192:195], v231 offset:56320
	global_load_lds_dwordx4 v[176:177], off
	v_lshl_add_u64 v[176:177], v[214:215], 0, s[24:25]
	s_mov_b32 m0, s19
	s_nop 0
	global_load_lds_dwordx4 v[176:177], off
	s_barrier
	s_waitcnt lgkmcnt(0)
	s_waitcnt lgkmcnt(0)
	v_mfma_f32_16x16x32_bf16 v[62:65], v[130:133], v[156:159], v[62:65]
	v_mfma_f32_16x16x32_bf16 v[58:61], v[138:141], v[156:159], v[58:61]
	v_mfma_f32_16x16x32_bf16 v[46:49], v[130:133], v[164:167], v[46:49]
	v_mfma_f32_16x16x32_bf16 v[42:45], v[138:141], v[164:167], v[42:45]
	v_mfma_f32_16x16x32_bf16 v[30:33], v[130:133], v[172:175], v[30:33]
	v_mfma_f32_16x16x32_bf16 v[26:29], v[138:141], v[172:175], v[26:29]
	v_mfma_f32_16x16x32_bf16 v[14:17], v[130:133], v[188:191], v[14:17]
	v_mfma_f32_16x16x32_bf16 v[10:13], v[138:141], v[188:191], v[10:13]
	v_mfma_f32_16x16x32_bf16 v[62:65], v[134:137], v[160:163], v[62:65]
	v_mfma_f32_16x16x32_bf16 v[58:61], v[142:145], v[160:163], v[58:61]
	v_mfma_f32_16x16x32_bf16 v[46:49], v[134:137], v[168:171], v[46:49]
	v_mfma_f32_16x16x32_bf16 v[42:45], v[142:145], v[168:171], v[42:45]
	v_mfma_f32_16x16x32_bf16 v[30:33], v[134:137], v[184:187], v[30:33]
	v_mfma_f32_16x16x32_bf16 v[26:29], v[142:145], v[184:187], v[26:29]
	v_mfma_f32_16x16x32_bf16 v[14:17], v[134:137], v[192:195], v[14:17]
	v_mfma_f32_16x16x32_bf16 v[10:13], v[142:145], v[192:195], v[10:13]
	s_barrier
	s_add_u32 s6, s62, 0x40080
	s_addc_u32 s7, s63, 0
	s_add_i32 s33, s90, s11
	v_lshl_add_u64 v[130:131], s[6:7], 0, v[146:147]
	s_mov_b32 m0, s33
	s_nop 0
	global_load_lds_dwordx4 v[130:131], off
	v_lshl_add_u64 v[130:131], s[6:7], 0, v[148:149]
	s_add_i32 m0, s33, 0x2000
	s_nop 0
	global_load_lds_dwordx4 v[130:131], off
	s_waitcnt vmcnt(6)
	s_barrier
	v_mfma_f32_16x16x32_bf16 v[54:57], v[196:199], v[156:159], v[54:57]
	v_mfma_f32_16x16x32_bf16 v[50:53], v[204:207], v[156:159], v[50:53]
	v_mfma_f32_16x16x32_bf16 v[38:41], v[196:199], v[164:167], v[38:41]
	v_mfma_f32_16x16x32_bf16 v[34:37], v[204:207], v[164:167], v[34:37]
	v_mfma_f32_16x16x32_bf16 v[22:25], v[196:199], v[172:175], v[22:25]
	v_mfma_f32_16x16x32_bf16 v[18:21], v[204:207], v[172:175], v[18:21]
	v_mfma_f32_16x16x32_bf16 v[6:9], v[196:199], v[188:191], v[6:9]
	v_mfma_f32_16x16x32_bf16 v[2:5], v[204:207], v[188:191], v[2:5]
	v_mfma_f32_16x16x32_bf16 v[54:57], v[200:203], v[160:163], v[54:57]
	v_mfma_f32_16x16x32_bf16 v[50:53], v[208:211], v[160:163], v[50:53]
	v_mfma_f32_16x16x32_bf16 v[38:41], v[200:203], v[168:171], v[38:41]
	v_mfma_f32_16x16x32_bf16 v[34:37], v[208:211], v[168:171], v[34:37]
	v_mfma_f32_16x16x32_bf16 v[22:25], v[200:203], v[184:187], v[22:25]
	v_mfma_f32_16x16x32_bf16 v[18:21], v[208:211], v[184:187], v[18:21]
	v_mfma_f32_16x16x32_bf16 v[6:9], v[200:203], v[192:195], v[6:9]
	v_mfma_f32_16x16x32_bf16 v[2:5], v[208:211], v[192:195], v[2:5]
	s_add_i32 vcc_hi, vcc_hi, 2
	s_add_u32 s2, s2, 0x100
	s_addc_u32 s3, s3, 0
	s_add_u32 s69, s69, 0x100
	s_addc_u32 vcc_lo, vcc_lo, 0
	s_cmp_gt_u32 vcc_hi, 13
	s_barrier

.LBB0_519:
	s_lshl_b32 s0, s28, 26
	s_add_u32 s0, s18, s0
	s_addc_u32 s1, s19, 0
	s_add_u32 s0, s0, 0x3c00000
	v_lshrrev_b32_e32 v17, 1, v13
	s_addc_u32 s1, s1, 0
	v_and_b32_e32 v17, 24, v17
	s_add_u32 s40, s18, 0x19c00000
	v_and_b32_e32 v16, 15, v13
	v_lshlrev_b32_e32 v18, 1, v17
	v_lshlrev_b32_e32 v13, 2, v13
	s_addc_u32 s41, s19, 0
	s_and_b32 s6, s20, 3
	v_lshl_or_b32 v179, s21, 6, v16
	v_lshl_or_b32 v16, v16, 6, v18
	s_lshl_b32 s7, s21, 13
	v_and_b32_e32 v13, 32, v13
	v_bitop3_b32 v18, v16, s7, v13 bitop3:0xde
	s_lshl_b32 s7, s6, 12
	s_add_i32 m0, s3, 0x18000
	v_lshl_add_u64 v[8:9], v[8:9], 0, s[24:25]
	v_bitop3_b32 v184, v16, s7, v13 bitop3:0xde
	s_waitcnt vmcnt(4)
	s_barrier
	global_load_lds_dwordx4 v[8:9], off
	v_lshl_add_u64 v[6:7], v[6:7], 0, s[24:25]
	s_add_i32 m0, s3, 0x1a000
	s_add_i32 s7, s3, 0x8000
	s_add_i32 s18, s3, 0xa000
	global_load_lds_dwordx4 v[6:7], off
	v_lshl_add_u64 v[4:5], v[4:5], 0, s[24:25]
	s_mov_b32 m0, s7
	s_add_u32 s20, s90, 0x20080
	global_load_lds_dwordx4 v[4:5], off
	v_lshl_add_u64 v[2:3], v[2:3], 0, s[24:25]
	s_mov_b32 m0, s18
	s_addc_u32 s21, s91, 0
	global_load_lds_dwordx4 v[2:3], off
	s_add_i32 m0, s3, 0x1c000
	v_lshl_add_u64 v[2:3], s[20:21], 0, v[162:163]
	global_load_lds_dwordx4 v[2:3], off
	v_lshl_add_u64 v[2:3], s[20:21], 0, v[164:165]
	s_add_i32 m0, s3, 0x1e000
	v_or_b32_e32 v186, 16, v179
	global_load_lds_dwordx4 v[2:3], off
	v_lshlrev_b32_e32 v2, 8, v179
	v_and_b32_e32 v185, 0xcf00, v2
	v_lshlrev_b32_e32 v2, 8, v186
	v_or_b32_e32 v188, 32, v179
	v_and_b32_e32 v187, 0xdf00, v2
	v_lshlrev_b32_e32 v2, 8, v188
	v_or_b32_e32 v190, 48, v179
	v_and_b32_e32 v189, 0xef00, v2
	v_lshlrev_b32_e32 v2, 8, v190
	v_add_u32_e32 v192, 0x80, v179
	v_and_b32_e32 v191, 0xff00, v2
	v_lshlrev_b32_e32 v2, 8, v192
	v_add_u32_e32 v194, 0x90, v179
	v_and_b32_e32 v193, 0xcf00, v2
	v_lshlrev_b32_e32 v2, 8, v194
	v_add_u32_e32 v196, 0xa0, v179
	v_and_b32_e32 v195, 0xdf00, v2
	v_lshlrev_b32_e32 v2, 8, v196
	v_add_u32_e32 v198, 0xb0, v179
	v_and_b32_e32 v197, 0xef00, v2
	v_lshlrev_b32_e32 v2, 8, v198
	v_and_b32_e32 v199, 0xff00, v2
	v_lshlrev_b32_e32 v2, 13, v0
	v_and_b32_e32 v2, 0xffffc000, v2
	v_lshl_add_u32 v2, v10, 10, v2
	v_and_b32_e32 v0, 1, v0
	v_lshl_or_b32 v0, v0, 6, v2
	v_lshl_add_u32 v166, v11, 1, v0
	v_lshlrev_b32_e32 v0, 13, v12
	v_and_b32_e32 v0, 0xffffc000, v0
	s_waitcnt vmcnt(6)
	v_lshl_add_u32 v0, v14, 10, v0
	v_and_b32_e32 v2, 1, v12
	v_lshl_or_b32 v0, v2, 6, v0
	s_ashr_i32 s19, s8, 31
	v_lshl_or_b32 v200, s6, 6, v17
	v_mov_b32_e32 v167, v1
	v_lshl_add_u32 v168, v15, 1, v0
	v_mov_b32_e32 v169, v1
	s_mov_b32 s20, 0
	v_add_u32_e32 v201, 0, v18
	s_barrier
	s_branch .LBB0_521
.LBB0_520:
	s_waitcnt vmcnt(0)
	v_lshlrev_b32_e32 v68, 16, v62
	v_and_b32_e32 v69, 0xffff0000, v62
	v_lshlrev_b32_e32 v62, 16, v63
	v_and_b32_e32 v63, 0xffff0000, v63
	v_pk_mul_f32 v[68:69], v[174:175], v[68:69]
	v_lshlrev_b32_e32 v70, 16, v58
	v_and_b32_e32 v71, 0xffff0000, v58
	v_pk_mul_f32 v[62:63], v[174:175], v[62:63]
	v_lshlrev_b32_e32 v58, 16, v59
	v_and_b32_e32 v59, 0xffff0000, v59
	v_pk_fma_f32 v[30:31], v[30:31], v[70:71], v[68:69]
	v_pk_fma_f32 v[32:33], v[32:33], v[58:59], v[62:63]
	v_cvt_pk_bf16_f32 v30, v30, v31
	v_cvt_pk_bf16_f32 v31, v32, v33
	v_lshlrev_b32_e32 v32, 16, v64
	v_and_b32_e32 v33, 0xffff0000, v64
	v_pk_mul_f32 v[32:33], v[174:175], v[32:33]
	v_lshlrev_b32_e32 v58, 16, v60
	v_and_b32_e32 v59, 0xffff0000, v60
	v_pk_fma_f32 v[26:27], v[26:27], v[58:59], v[32:33]
	v_lshlrev_b32_e32 v58, 16, v61
	v_cvt_pk_bf16_f32 v32, v26, v27
	v_lshlrev_b32_e32 v26, 16, v65
	v_and_b32_e32 v27, 0xffff0000, v65
	v_pk_mul_f32 v[26:27], v[174:175], v[26:27]
	v_and_b32_e32 v59, 0xffff0000, v61
	v_pk_fma_f32 v[26:27], v[28:29], v[58:59], v[26:27]
	v_lshlrev_b32_e32 v28, 16, v46
	v_cvt_pk_bf16_f32 v33, v26, v27
	v_lshlrev_b32_e32 v26, 16, v50
	v_and_b32_e32 v27, 0xffff0000, v50
	v_pk_mul_f32 v[26:27], v[174:175], v[26:27]
	v_and_b32_e32 v29, 0xffff0000, v46
	v_pk_fma_f32 v[22:23], v[22:23], v[28:29], v[26:27]
	v_lshlrev_b32_e32 v26, 16, v51
	v_and_b32_e32 v27, 0xffff0000, v51
	v_pk_mul_f32 v[26:27], v[174:175], v[26:27]
	v_lshlrev_b32_e32 v28, 16, v47
	v_and_b32_e32 v29, 0xffff0000, v47
	v_pk_fma_f32 v[24:25], v[24:25], v[28:29], v[26:27]
	v_cvt_pk_bf16_f32 v22, v22, v23
	v_cvt_pk_bf16_f32 v23, v24, v25
	v_lshlrev_b32_e32 v24, 16, v52
	v_and_b32_e32 v25, 0xffff0000, v52
	v_pk_mul_f32 v[24:25], v[174:175], v[24:25]
	v_lshlrev_b32_e32 v26, 16, v48
	v_and_b32_e32 v27, 0xffff0000, v48
	v_add_u32_e32 v66, 0xa0, v170
	v_pk_fma_f32 v[18:19], v[18:19], v[26:27], v[24:25]
	v_ashrrev_i32_e32 v67, 31, v66
	v_cvt_pk_bf16_f32 v24, v18, v19
	v_lshlrev_b32_e32 v18, 16, v53
	v_and_b32_e32 v19, 0xffff0000, v53
	v_lshlrev_b64 v[66:67], 11, v[66:67]
	v_pk_mul_f32 v[18:19], v[174:175], v[18:19]
	v_lshlrev_b32_e32 v26, 16, v49
	v_and_b32_e32 v27, 0xffff0000, v49
	v_lshl_add_u64 v[66:67], s[0:1], 0, v[66:67]
	v_mov_b32_e32 v173, v1
	v_pk_fma_f32 v[18:19], v[20:21], v[26:27], v[18:19]
	v_lshl_add_u64 v[66:67], v[66:67], 0, v[172:173]
	v_cvt_pk_bf16_f32 v25, v18, v19
	v_lshlrev_b32_e32 v20, 16, v54
	v_and_b32_e32 v21, 0xffff0000, v54
	global_store_dwordx4 v[66:67], v[22:25], off offset:64
	v_pk_mul_f32 v[20:21], v[174:175], v[20:21]
	v_add_u32_e32 v18, 0xb0, v170
	v_lshlrev_b32_e32 v22, 16, v42
	v_and_b32_e32 v23, 0xffff0000, v42
	v_pk_fma_f32 v[14:15], v[14:15], v[22:23], v[20:21]
	v_lshlrev_b32_e32 v20, 16, v55
	v_and_b32_e32 v21, 0xffff0000, v55
	v_pk_mul_f32 v[20:21], v[174:175], v[20:21]
	v_lshlrev_b32_e32 v22, 16, v43
	v_and_b32_e32 v23, 0xffff0000, v43
	v_pk_fma_f32 v[16:17], v[16:17], v[22:23], v[20:21]
	v_cvt_pk_bf16_f32 v14, v14, v15
	v_cvt_pk_bf16_f32 v15, v16, v17
	v_lshlrev_b32_e32 v16, 16, v56
	v_and_b32_e32 v17, 0xffff0000, v56
	v_pk_mul_f32 v[16:17], v[174:175], v[16:17]
	v_lshlrev_b32_e32 v20, 16, v44
	v_and_b32_e32 v21, 0xffff0000, v44
	v_pk_fma_f32 v[10:11], v[10:11], v[20:21], v[16:17]
	v_lshlrev_b32_e32 v20, 16, v45
	v_cvt_pk_bf16_f32 v16, v10, v11
	v_lshlrev_b32_e32 v10, 16, v57
	v_and_b32_e32 v11, 0xffff0000, v57
	v_pk_mul_f32 v[10:11], v[174:175], v[10:11]
	v_and_b32_e32 v21, 0xffff0000, v45
	v_pk_fma_f32 v[10:11], v[12:13], v[20:21], v[10:11]
	v_lshlrev_b32_e32 v12, 16, v38
	v_cvt_pk_bf16_f32 v17, v10, v11
	v_lshlrev_b32_e32 v10, 16, v34
	v_and_b32_e32 v11, 0xffff0000, v34
	v_pk_mul_f32 v[10:11], v[174:175], v[10:11]
	v_and_b32_e32 v13, 0xffff0000, v38
	v_pk_fma_f32 v[6:7], v[6:7], v[12:13], v[10:11]
	v_lshlrev_b32_e32 v10, 16, v35
	v_and_b32_e32 v11, 0xffff0000, v35
	v_pk_mul_f32 v[10:11], v[174:175], v[10:11]
	v_lshlrev_b32_e32 v12, 16, v39
	v_and_b32_e32 v13, 0xffff0000, v39
	v_pk_fma_f32 v[8:9], v[8:9], v[12:13], v[10:11]
	v_cvt_pk_bf16_f32 v6, v6, v7
	v_cvt_pk_bf16_f32 v7, v8, v9
	v_lshlrev_b32_e32 v8, 16, v36
	v_and_b32_e32 v9, 0xffff0000, v36
	v_pk_mul_f32 v[8:9], v[174:175], v[8:9]
	v_lshlrev_b32_e32 v10, 16, v40
	v_and_b32_e32 v11, 0xffff0000, v40
	v_pk_fma_f32 v[2:3], v[2:3], v[10:11], v[8:9]
	v_ashrrev_i32_e32 v19, 31, v18
	v_cvt_pk_bf16_f32 v8, v2, v3
	v_lshlrev_b32_e32 v2, 16, v37
	v_and_b32_e32 v3, 0xffff0000, v37
	v_lshlrev_b64 v[18:19], 11, v[18:19]
	v_pk_mul_f32 v[2:3], v[174:175], v[2:3]
	v_lshlrev_b32_e32 v10, 16, v41
	v_and_b32_e32 v11, 0xffff0000, v41
	v_lshl_add_u64 v[18:19], s[0:1], 0, v[18:19]
	v_pk_fma_f32 v[2:3], v[4:5], v[10:11], v[2:3]
	v_lshl_add_u64 v[18:19], v[18:19], 0, v[172:173]
	v_cvt_pk_bf16_f32 v9, v2, v3
	s_and_b64 vcc, exec, s[36:37]
	s_mov_b32 s38, s68
	s_mov_b32 s2, s46
	s_mov_b64 s[90:91], s[88:89]
	s_mov_b64 s[62:63], s[84:85]
	global_store_dwordx4 v[66:67], v[30:33], off
	global_store_dwordx4 v[18:19], v[14:17], off
	global_store_dwordx4 v[18:19], v[6:9], off offset:64
	s_cmpk_gt_u32 s9, 0xff
	s_cbranch_scc0 .Lepi1_branch
	s_barrier

.LBB0_527:
	s_ashr_i32 s47, s46, 31
	s_lshl_b64 s[22:23], s[46:47], 18
	v_cmp_lt_i64_e32 vcc, s[84:85], v[182:183]
	s_add_u32 s84, s10, s22
	s_addc_u32 s85, s11, s23
	s_and_b64 s[22:23], vcc, exec
	s_cselect_b32 s21, s85, s63
	s_cselect_b32 s22, s84, s62
	s_ashr_i32 s69, s68, 31
	s_lshl_b64 s[72:73], s[68:69], 18
	s_add_u32 s88, s12, s72
	s_addc_u32 s89, s13, s73
	s_and_b64 s[72:73], vcc, exec
	s_cselect_b32 s23, s89, s91
	s_cselect_b32 s39, s88, s90
	s_add_u32 s62, s62, 0x20080
	s_addc_u32 s63, s63, 0
	s_add_u32 s47, s90, 0x100
	s_addc_u32 s48, s91, 0
	s_mov_b32 s69, -2
	s_add_u32 s6, s62, 0xfffe0080
	s_addc_u32 s33, s63, -1
	s_add_i32 s72, 0, 0x10000
	v_add_u32_e32 v0, s72, v184
	ds_read_b128 v[130:133], v0
	ds_read_b128 v[134:137], v0 offset:1024
	ds_read_b128 v[138:141], v0 offset:2048
	ds_read_b128 v[142:145], v0 offset:3072
	s_cmp_eq_u32 s69, 4
	s_cselect_b32 vcc_hi, s21, s33
	s_cselect_b32 vcc_lo, s22, s6
	s_cselect_b32 s91, s23, s48
	s_cselect_b32 s90, s39, s47
	v_lshl_add_u64 v[180:181], s[62:63], 0, v[166:167]
	s_add_i32 m0, s3, 0xc000
	ds_read_b128 v[146:149], v201
	ds_read_b128 v[150:153], v201 offset:1024
	ds_read_b128 v[154:157], v201 offset:2048
	ds_read_b128 v[158:161], v201 offset:3072
	ds_read_b128 v[170:173], v201 offset:4096
	ds_read_b128 v[174:177], v201 offset:5120
	ds_read_b128 v[202:205], v201 offset:6144
	ds_read_b128 v[206:209], v201 offset:7168
	global_load_lds_dwordx4 v[180:181], off
	v_lshl_add_u64 v[180:181], s[62:63], 0, v[168:169]
	s_add_i32 m0, s3, 0xe000
	s_nop 0
	global_load_lds_dwordx4 v[180:181], off
	s_waitcnt lgkmcnt(8)
	s_barrier
	s_waitcnt lgkmcnt(0)
	s_waitcnt lgkmcnt(0)
	v_mfma_f32_16x16x32_bf16 v[126:129], v[130:133], v[146:149], 0
	v_mfma_f32_16x16x32_bf16 v[122:125], v[138:141], v[146:149], 0
	v_mfma_f32_16x16x32_bf16 v[110:113], v[130:133], v[154:157], 0
	v_mfma_f32_16x16x32_bf16 v[106:109], v[138:141], v[154:157], 0
	v_mfma_f32_16x16x32_bf16 v[94:97], v[130:133], v[170:173], 0
	v_mfma_f32_16x16x32_bf16 v[90:93], v[138:141], v[170:173], 0
	v_mfma_f32_16x16x32_bf16 v[78:81], v[130:133], v[202:205], 0
	v_mfma_f32_16x16x32_bf16 v[74:77], v[138:141], v[202:205], 0
	v_mfma_f32_16x16x32_bf16 v[126:129], v[134:137], v[150:153], v[126:129]
	v_mfma_f32_16x16x32_bf16 v[122:125], v[142:145], v[150:153], v[122:125]
	v_mfma_f32_16x16x32_bf16 v[110:113], v[134:137], v[158:161], v[110:113]
	v_mfma_f32_16x16x32_bf16 v[106:109], v[142:145], v[158:161], v[106:109]
	v_mfma_f32_16x16x32_bf16 v[94:97], v[134:137], v[174:177], v[94:97]
	v_mfma_f32_16x16x32_bf16 v[90:93], v[142:145], v[174:177], v[90:93]
	v_mfma_f32_16x16x32_bf16 v[78:81], v[134:137], v[206:209], v[78:81]
	v_mfma_f32_16x16x32_bf16 v[74:77], v[142:145], v[206:209], v[74:77]
	s_barrier
	s_add_i32 s6, 0, 0x14000
	s_add_i32 s33, s72, s14
	v_add_u32_e32 v0, s6, v184
	v_lshl_add_u64 v[180:181], s[90:91], 0, v[162:163]
	s_mov_b32 m0, s33
	ds_read_b128 v[210:213], v0
	ds_read_b128 v[214:217], v0 offset:1024
	ds_read_b128 v[218:221], v0 offset:2048
	ds_read_b128 v[222:225], v0 offset:3072
	global_load_lds_dwordx4 v[180:181], off
	v_lshl_add_u64 v[226:227], s[90:91], 0, v[164:165]
	s_add_i32 m0, s33, 0x2000
	s_nop 0
	global_load_lds_dwordx4 v[226:227], off
	s_barrier
	s_waitcnt lgkmcnt(0)
	s_waitcnt lgkmcnt(0)
	v_mfma_f32_16x16x32_bf16 v[118:121], v[210:213], v[146:149], 0
	v_mfma_f32_16x16x32_bf16 v[114:117], v[218:221], v[146:149], 0
	v_mfma_f32_16x16x32_bf16 v[102:105], v[210:213], v[154:157], 0
	v_mfma_f32_16x16x32_bf16 v[98:101], v[218:221], v[154:157], 0
	v_mfma_f32_16x16x32_bf16 v[86:89], v[210:213], v[170:173], 0
	v_mfma_f32_16x16x32_bf16 v[82:85], v[218:221], v[170:173], 0
	v_mfma_f32_16x16x32_bf16 v[70:73], v[210:213], v[202:205], 0
	v_mfma_f32_16x16x32_bf16 v[66:69], v[218:221], v[202:205], 0
	v_mfma_f32_16x16x32_bf16 v[118:121], v[214:217], v[150:153], v[118:121]
	v_mfma_f32_16x16x32_bf16 v[114:117], v[222:225], v[150:153], v[114:117]
	v_mfma_f32_16x16x32_bf16 v[102:105], v[214:217], v[158:161], v[102:105]
	v_mfma_f32_16x16x32_bf16 v[98:101], v[222:225], v[158:161], v[98:101]
	v_mfma_f32_16x16x32_bf16 v[86:89], v[214:217], v[174:177], v[86:89]
	v_mfma_f32_16x16x32_bf16 v[82:85], v[222:225], v[174:177], v[82:85]
	v_mfma_f32_16x16x32_bf16 v[70:73], v[214:217], v[206:209], v[70:73]
	v_mfma_f32_16x16x32_bf16 v[66:69], v[222:225], v[206:209], v[66:69]
	s_mov_b32 m0, s3
	v_lshl_add_u64 v[240:241], vcc, 0, v[162:163]
	s_barrier
	ds_read_b128 v[146:149], v201 offset:16384
	ds_read_b128 v[150:153], v201 offset:17408
	ds_read_b128 v[154:157], v201 offset:18432
	ds_read_b128 v[158:161], v201 offset:19456
	ds_read_b128 v[170:173], v201 offset:20480
	ds_read_b128 v[174:177], v201 offset:21504
	ds_read_b128 v[202:205], v201 offset:22528
	ds_read_b128 v[206:209], v201 offset:23552
	global_load_lds_dwordx4 v[240:241], off
	v_lshl_add_u64 v[244:245], vcc, 0, v[164:165]
	s_mov_b32 m0, s15
	s_nop 0
	global_load_lds_dwordx4 v[244:245], off
	s_barrier
	s_waitcnt lgkmcnt(0)
	s_waitcnt lgkmcnt(0)
	v_mfma_f32_16x16x32_bf16 v[62:65], v[130:133], v[146:149], 0
	v_mfma_f32_16x16x32_bf16 v[58:61], v[138:141], v[146:149], 0
	v_mfma_f32_16x16x32_bf16 v[46:49], v[130:133], v[154:157], 0
	v_mfma_f32_16x16x32_bf16 v[42:45], v[138:141], v[154:157], 0
	v_mfma_f32_16x16x32_bf16 v[30:33], v[130:133], v[170:173], 0
	v_mfma_f32_16x16x32_bf16 v[26:29], v[138:141], v[170:173], 0
	v_mfma_f32_16x16x32_bf16 v[14:17], v[130:133], v[202:205], 0
	v_mfma_f32_16x16x32_bf16 v[10:13], v[138:141], v[202:205], 0
	v_mfma_f32_16x16x32_bf16 v[62:65], v[134:137], v[150:153], v[62:65]
	v_mfma_f32_16x16x32_bf16 v[58:61], v[142:145], v[150:153], v[58:61]
	v_mfma_f32_16x16x32_bf16 v[46:49], v[134:137], v[158:161], v[46:49]
	v_mfma_f32_16x16x32_bf16 v[42:45], v[142:145], v[158:161], v[42:45]
	v_mfma_f32_16x16x32_bf16 v[30:33], v[134:137], v[174:177], v[30:33]
	v_mfma_f32_16x16x32_bf16 v[26:29], v[142:145], v[174:177], v[26:29]
	v_mfma_f32_16x16x32_bf16 v[14:17], v[134:137], v[206:209], v[14:17]
	v_mfma_f32_16x16x32_bf16 v[10:13], v[142:145], v[206:209], v[10:13]
	s_barrier
	s_add_u32 s72, s90, 0x20000
	s_addc_u32 s73, s91, 0
	s_add_i32 s6, s6, s14
	v_lshl_add_u64 v[130:131], s[72:73], 0, v[162:163]
	s_mov_b32 m0, s6
	s_nop 0
	global_load_lds_dwordx4 v[130:131], off
	v_lshl_add_u64 v[130:131], s[72:73], 0, v[164:165]
	s_add_i32 m0, s6, 0x2000
	s_nop 0
	global_load_lds_dwordx4 v[130:131], off
	s_waitcnt vmcnt(6)
	s_barrier
	v_mfma_f32_16x16x32_bf16 v[54:57], v[210:213], v[146:149], 0
	v_mfma_f32_16x16x32_bf16 v[50:53], v[218:221], v[146:149], 0
	v_mfma_f32_16x16x32_bf16 v[38:41], v[210:213], v[154:157], 0
	v_mfma_f32_16x16x32_bf16 v[34:37], v[218:221], v[154:157], 0
	v_mfma_f32_16x16x32_bf16 v[22:25], v[210:213], v[170:173], 0
	v_mfma_f32_16x16x32_bf16 v[18:21], v[218:221], v[170:173], 0
	v_mfma_f32_16x16x32_bf16 v[6:9], v[210:213], v[202:205], 0
	v_mfma_f32_16x16x32_bf16 v[2:5], v[218:221], v[202:205], 0
	v_mfma_f32_16x16x32_bf16 v[54:57], v[214:217], v[150:153], v[54:57]
	v_mfma_f32_16x16x32_bf16 v[50:53], v[222:225], v[150:153], v[50:53]
	v_mfma_f32_16x16x32_bf16 v[38:41], v[214:217], v[158:161], v[38:41]
	v_mfma_f32_16x16x32_bf16 v[34:37], v[222:225], v[158:161], v[34:37]
	v_mfma_f32_16x16x32_bf16 v[22:25], v[214:217], v[174:177], v[22:25]
	v_mfma_f32_16x16x32_bf16 v[18:21], v[222:225], v[174:177], v[18:21]
	v_mfma_f32_16x16x32_bf16 v[6:9], v[214:217], v[206:209], v[6:9]
	v_mfma_f32_16x16x32_bf16 v[2:5], v[222:225], v[206:209], v[2:5]
	s_add_i32 s6, 0, 0x18000
	v_add_u32_e32 v0, s6, v184
	s_barrier
	ds_read_b128 v[130:133], v0
	ds_read_b128 v[134:137], v0 offset:1024
	ds_read_b128 v[138:141], v0 offset:2048
	ds_read_b128 v[142:145], v0 offset:3072
	s_add_u32 s72, vcc_lo, 0x20000
	s_addc_u32 s73, vcc_hi, 0
	s_mov_b32 m0, s16
	v_lshl_add_u64 v[210:211], s[72:73], 0, v[162:163]
	ds_read_b128 v[146:149], v201 offset:32768
	ds_read_b128 v[150:153], v201 offset:33792
	ds_read_b128 v[154:157], v201 offset:34816
	ds_read_b128 v[158:161], v201 offset:35840
	ds_read_b128 v[170:173], v201 offset:36864
	ds_read_b128 v[174:177], v201 offset:37888
	ds_read_b128 v[202:205], v201 offset:38912
	ds_read_b128 v[206:209], v201 offset:39936
	global_load_lds_dwordx4 v[210:211], off
	v_lshl_add_u64 v[210:211], s[72:73], 0, v[164:165]
	s_mov_b32 m0, s17
	s_nop 0
	global_load_lds_dwordx4 v[210:211], off
	s_waitcnt lgkmcnt(8)
	s_barrier
	s_waitcnt lgkmcnt(0)
	s_waitcnt lgkmcnt(0)
	v_mfma_f32_16x16x32_bf16 v[126:129], v[130:133], v[146:149], v[126:129]
	v_mfma_f32_16x16x32_bf16 v[122:125], v[138:141], v[146:149], v[122:125]
	v_mfma_f32_16x16x32_bf16 v[110:113], v[130:133], v[154:157], v[110:113]
	v_mfma_f32_16x16x32_bf16 v[106:109], v[138:141], v[154:157], v[106:109]
	v_mfma_f32_16x16x32_bf16 v[94:97], v[130:133], v[170:173], v[94:97]
	v_mfma_f32_16x16x32_bf16 v[90:93], v[138:141], v[170:173], v[90:93]
	v_mfma_f32_16x16x32_bf16 v[78:81], v[130:133], v[202:205], v[78:81]
	v_mfma_f32_16x16x32_bf16 v[74:77], v[138:141], v[202:205], v[74:77]
	v_mfma_f32_16x16x32_bf16 v[126:129], v[134:137], v[150:153], v[126:129]
	v_mfma_f32_16x16x32_bf16 v[122:125], v[142:145], v[150:153], v[122:125]
	v_mfma_f32_16x16x32_bf16 v[110:113], v[134:137], v[158:161], v[110:113]
	v_mfma_f32_16x16x32_bf16 v[106:109], v[142:145], v[158:161], v[106:109]
	v_mfma_f32_16x16x32_bf16 v[94:97], v[134:137], v[174:177], v[94:97]
	v_mfma_f32_16x16x32_bf16 v[90:93], v[142:145], v[174:177], v[90:93]
	v_mfma_f32_16x16x32_bf16 v[78:81], v[134:137], v[206:209], v[78:81]
	v_mfma_f32_16x16x32_bf16 v[74:77], v[142:145], v[206:209], v[74:77]
	s_barrier
	s_add_i32 s33, 0, 0x1c000
	s_add_i32 s6, s6, s14
	v_add_u32_e32 v0, s33, v184
	v_lshl_add_u64 v[180:181], v[180:181], 0, s[24:25]
	s_mov_b32 m0, s6
	ds_read_b128 v[210:213], v0
	ds_read_b128 v[214:217], v0 offset:1024
	ds_read_b128 v[218:221], v0 offset:2048
	ds_read_b128 v[222:225], v0 offset:3072
	global_load_lds_dwordx4 v[180:181], off
	v_lshl_add_u64 v[180:181], v[226:227], 0, s[24:25]
	s_add_i32 m0, s6, 0x2000
	s_nop 0
	global_load_lds_dwordx4 v[180:181], off
	s_barrier
	s_waitcnt lgkmcnt(0)
	s_waitcnt lgkmcnt(0)
	v_mfma_f32_16x16x32_bf16 v[118:121], v[210:213], v[146:149], v[118:121]
	v_mfma_f32_16x16x32_bf16 v[114:117], v[218:221], v[146:149], v[114:117]
	v_mfma_f32_16x16x32_bf16 v[102:105], v[210:213], v[154:157], v[102:105]
	v_mfma_f32_16x16x32_bf16 v[98:101], v[218:221], v[154:157], v[98:101]
	v_mfma_f32_16x16x32_bf16 v[86:89], v[210:213], v[170:173], v[86:89]
	v_mfma_f32_16x16x32_bf16 v[82:85], v[218:221], v[170:173], v[82:85]
	v_mfma_f32_16x16x32_bf16 v[70:73], v[210:213], v[202:205], v[70:73]
	v_mfma_f32_16x16x32_bf16 v[66:69], v[218:221], v[202:205], v[66:69]
	v_mfma_f32_16x16x32_bf16 v[118:121], v[214:217], v[150:153], v[118:121]
	v_mfma_f32_16x16x32_bf16 v[114:117], v[222:225], v[150:153], v[114:117]
	v_mfma_f32_16x16x32_bf16 v[102:105], v[214:217], v[158:161], v[102:105]
	v_mfma_f32_16x16x32_bf16 v[98:101], v[222:225], v[158:161], v[98:101]
	v_mfma_f32_16x16x32_bf16 v[86:89], v[214:217], v[174:177], v[86:89]
	v_mfma_f32_16x16x32_bf16 v[82:85], v[222:225], v[174:177], v[82:85]
	v_mfma_f32_16x16x32_bf16 v[70:73], v[214:217], v[206:209], v[70:73]
	v_mfma_f32_16x16x32_bf16 v[66:69], v[222:225], v[206:209], v[66:69]
	s_mov_b32 m0, s7
	v_lshl_add_u64 v[180:181], v[240:241], 0, s[24:25]
	s_barrier
	ds_read_b128 v[146:149], v201 offset:49152
	ds_read_b128 v[150:153], v201 offset:50176
	ds_read_b128 v[154:157], v201 offset:51200
	ds_read_b128 v[158:161], v201 offset:52224
	ds_read_b128 v[170:173], v201 offset:53248
	ds_read_b128 v[174:177], v201 offset:54272
	ds_read_b128 v[202:205], v201 offset:55296
	ds_read_b128 v[206:209], v201 offset:56320
	global_load_lds_dwordx4 v[180:181], off
	v_lshl_add_u64 v[180:181], v[244:245], 0, s[24:25]
	s_mov_b32 m0, s18
	s_nop 0
	global_load_lds_dwordx4 v[180:181], off
	s_barrier
	s_waitcnt lgkmcnt(0)
	s_waitcnt lgkmcnt(0)
	v_mfma_f32_16x16x32_bf16 v[62:65], v[130:133], v[146:149], v[62:65]
	v_mfma_f32_16x16x32_bf16 v[58:61], v[138:141], v[146:149], v[58:61]
	v_mfma_f32_16x16x32_bf16 v[46:49], v[130:133], v[154:157], v[46:49]
	v_mfma_f32_16x16x32_bf16 v[42:45], v[138:141], v[154:157], v[42:45]
	v_mfma_f32_16x16x32_bf16 v[30:33], v[130:133], v[170:173], v[30:33]
	v_mfma_f32_16x16x32_bf16 v[26:29], v[138:141], v[170:173], v[26:29]
	v_mfma_f32_16x16x32_bf16 v[14:17], v[130:133], v[202:205], v[14:17]
	v_mfma_f32_16x16x32_bf16 v[10:13], v[138:141], v[202:205], v[10:13]
	v_mfma_f32_16x16x32_bf16 v[62:65], v[134:137], v[150:153], v[62:65]
	v_mfma_f32_16x16x32_bf16 v[58:61], v[142:145], v[150:153], v[58:61]
	v_mfma_f32_16x16x32_bf16 v[46:49], v[134:137], v[158:161], v[46:49]
	v_mfma_f32_16x16x32_bf16 v[42:45], v[142:145], v[158:161], v[42:45]
	v_mfma_f32_16x16x32_bf16 v[30:33], v[134:137], v[174:177], v[30:33]
	v_mfma_f32_16x16x32_bf16 v[26:29], v[142:145], v[174:177], v[26:29]
	v_mfma_f32_16x16x32_bf16 v[14:17], v[134:137], v[206:209], v[14:17]
	v_mfma_f32_16x16x32_bf16 v[10:13], v[142:145], v[206:209], v[10:13]
	s_barrier
	s_add_u32 s72, s90, 0x20080
	s_addc_u32 s73, s91, 0
	s_add_i32 s6, s33, s14
	v_lshl_add_u64 v[130:131], s[72:73], 0, v[162:163]
	s_mov_b32 m0, s6
	s_nop 0
	global_load_lds_dwordx4 v[130:131], off
	v_lshl_add_u64 v[130:131], s[72:73], 0, v[164:165]
	s_add_i32 m0, s6, 0x2000
	s_nop 0
	global_load_lds_dwordx4 v[130:131], off
	s_waitcnt vmcnt(6)
	s_barrier
	v_mfma_f32_16x16x32_bf16 v[54:57], v[210:213], v[146:149], v[54:57]
	v_mfma_f32_16x16x32_bf16 v[50:53], v[218:221], v[146:149], v[50:53]
	v_mfma_f32_16x16x32_bf16 v[38:41], v[210:213], v[154:157], v[38:41]
	v_mfma_f32_16x16x32_bf16 v[34:37], v[218:221], v[154:157], v[34:37]
	v_mfma_f32_16x16x32_bf16 v[22:25], v[210:213], v[170:173], v[22:25]
	v_mfma_f32_16x16x32_bf16 v[18:21], v[218:221], v[170:173], v[18:21]
	v_mfma_f32_16x16x32_bf16 v[6:9], v[210:213], v[202:205], v[6:9]
	v_mfma_f32_16x16x32_bf16 v[2:5], v[218:221], v[202:205], v[2:5]
	v_mfma_f32_16x16x32_bf16 v[54:57], v[214:217], v[150:153], v[54:57]
	v_mfma_f32_16x16x32_bf16 v[50:53], v[222:225], v[150:153], v[50:53]
	v_mfma_f32_16x16x32_bf16 v[38:41], v[214:217], v[158:161], v[38:41]
	v_mfma_f32_16x16x32_bf16 v[34:37], v[222:225], v[158:161], v[34:37]
	v_mfma_f32_16x16x32_bf16 v[22:25], v[214:217], v[174:177], v[22:25]
	v_mfma_f32_16x16x32_bf16 v[18:21], v[222:225], v[174:177], v[18:21]
	v_mfma_f32_16x16x32_bf16 v[6:9], v[214:217], v[206:209], v[6:9]
	v_mfma_f32_16x16x32_bf16 v[2:5], v[222:225], v[206:209], v[2:5]
	s_add_i32 s69, s69, 2
	s_add_u32 s62, s62, 0x100
	s_addc_u32 s63, s63, 0
	s_add_u32 s47, s47, 0x100
	s_addc_u32 s48, s48, 0
	s_cmp_gt_u32 s69, 5
	s_barrier

.LBB0_609:
	s_add_u32 s24, s16, 0x19c00000
	s_addc_u32 s25, s17, 0
	v_bfe_u32 v16, v8, 4, 2
	s_add_u32 s26, s16, 0x12000000
	v_and_b32_e32 v15, 15, v8
	v_lshlrev_b32_e32 v18, 4, v16
	v_lshlrev_b32_e32 v8, 2, v8
	s_addc_u32 s27, s17, 0
	s_and_b32 s3, s18, 3
	v_lshl_or_b32 v182, s19, 6, v15
	v_lshl_or_b32 v15, v15, 6, v18
	s_lshl_b32 s16, s19, 13
	v_and_b32_e32 v8, 32, v8
	s_mov_b64 s[28:29], 0x80
	v_bitop3_b32 v18, v15, s16, v8 bitop3:0xde
	s_lshl_b32 s16, s3, 12
	s_add_i32 m0, s11, 0x18000
	v_lshl_add_u64 v[6:7], v[6:7], 0, s[28:29]
	v_bitop3_b32 v183, v15, s16, v8 bitop3:0xde
	s_waitcnt vmcnt(4)
	s_barrier
	global_load_lds_dwordx4 v[6:7], off
	v_lshl_add_u64 v[4:5], v[4:5], 0, s[28:29]
	s_add_i32 m0, s11, 0x1a000
	s_add_i32 s16, s11, 0x8000
	s_add_i32 s17, s11, 0xa000
	global_load_lds_dwordx4 v[4:5], off
	v_lshl_add_u64 v[2:3], v[2:3], 0, s[28:29]
	s_mov_b32 m0, s16
	s_add_u32 s18, s52, 0x40080
	global_load_lds_dwordx4 v[2:3], off
	v_lshl_add_u64 v[0:1], v[0:1], 0, s[28:29]
	s_mov_b32 m0, s17
	s_addc_u32 s19, s53, 0
	global_load_lds_dwordx4 v[0:1], off
	s_add_i32 m0, s11, 0x1c000
	v_lshl_add_u64 v[0:1], s[18:19], 0, v[160:161]
	global_load_lds_dwordx4 v[0:1], off
	v_lshl_add_u64 v[0:1], s[18:19], 0, v[162:163]
	s_add_i32 m0, s11, 0x1e000
	v_lshlrev_b32_e32 v17, 3, v16
	global_load_lds_dwordx4 v[0:1], off
	v_lshlrev_b32_e32 v0, 14, v9
	v_and_b32_e32 v0, 0xffff8000, v0
	v_lshl_add_u32 v0, v10, 11, v0
	v_and_b32_e32 v1, 1, v9
	v_lshl_or_b32 v0, v1, 6, v0
	v_lshl_add_u32 v164, v11, 1, v0
	v_lshlrev_b32_e32 v0, 14, v12
	v_and_b32_e32 v0, 0xffff8000, v0
	s_waitcnt vmcnt(6)
	v_lshl_add_u32 v0, v13, 11, v0
	v_and_b32_e32 v1, 1, v12
	v_lshl_or_b32 v0, v1, 6, v0
	s_add_i32 s19, 0, 0x10000
	s_add_i32 s20, 0, 0x14000
	v_lshl_or_b32 v184, s3, 6, v17
	v_cmp_eq_u32_e64 s[36:37], 0, v16
	s_ashr_i32 s18, s4, 31
	v_mov_b32_e32 v165, v161
	v_lshl_add_u32 v166, v14, 1, v0
	v_mov_b32_e32 v167, v161
	v_mov_b64_e32 v[168:169], 0x400
	v_mov_b64_e32 v[170:171], 0x3ff
	v_add_u32_e32 v185, s19, v183
	v_add_u32_e32 v186, 0, v18
	v_add_u32_e32 v187, s20, v183
	s_barrier
	s_branch .LBB0_611
	s_nop 0
	s_nop 0
	s_nop 0
	s_nop 0
	s_nop 0
	s_nop 0
	s_nop 0
.LBB0_610:
	s_or_b64 exec, exec, s[2:3]
	s_and_b64 vcc, exec, s[38:39]
	s_mov_b32 s46, s34
	s_mov_b32 s2, s30
	s_mov_b64 s[52:53], s[42:43]
	s_mov_b64 s[48:49], s[40:41]
	s_cmpk_gt_u32 s5, 0xff
	s_cbranch_scc0 .Lepi1_out
	s_barrier

.LBB0_617:
	s_ashr_i32 s31, s30, 31
	s_lshl_b64 s[22:23], s[30:31], 19
	v_cmp_lt_i64_e32 vcc, s[40:41], v[168:169]
	s_add_u32 s40, s6, s22
	s_addc_u32 s41, s7, s23
	s_and_b64 s[22:23], vcc, exec
	s_cselect_b32 s3, s41, s49
	s_cselect_b32 s21, s40, s48
	s_ashr_i32 s35, s34, 31
	s_lshl_b64 s[22:23], s[34:35], 19
	s_add_u32 s42, s8, s22
	s_addc_u32 s43, s9, s23
	s_and_b64 s[22:23], vcc, exec
	s_cselect_b32 s22, s43, s53
	s_cselect_b32 s23, s42, s52
	s_add_u32 s48, s48, 0x40080
	s_addc_u32 s49, s49, 0
	s_add_u32 s31, s52, 0x100
	s_addc_u32 s33, s53, 0
	s_mov_b32 s35, -2
	s_waitcnt lgkmcnt(0)
	ds_read_b128 v[48:51], v185
	ds_read_b128 v[52:55], v185 offset:1024
	ds_read_b128 v[56:59], v185 offset:2048
	ds_read_b128 v[60:63], v185 offset:3072
	s_add_u32 s47, s48, 0xfffc0080
	s_addc_u32 s50, s49, -1
	s_cmp_eq_u32 s35, 12
	s_cselect_b32 s55, s3, s50
	s_cselect_b32 s54, s21, s47
	s_cselect_b32 s53, s22, s33
	s_cselect_b32 s52, s23, s31
	v_lshl_add_u64 v[180:181], s[48:49], 0, v[164:165]
	s_add_i32 m0, s11, 0xc000
	ds_read_b128 v[144:147], v186
	ds_read_b128 v[148:151], v186 offset:1024
	ds_read_b128 v[152:155], v186 offset:2048
	ds_read_b128 v[156:159], v186 offset:3072
	ds_read_b128 v[172:175], v186 offset:4096
	ds_read_b128 v[176:179], v186 offset:5120
	ds_read_b128 v[188:191], v186 offset:6144
	ds_read_b128 v[192:195], v186 offset:7168
	global_load_lds_dwordx4 v[180:181], off
	v_lshl_add_u64 v[180:181], s[48:49], 0, v[166:167]
	s_add_i32 m0, s11, 0xe000
	s_nop 0
	global_load_lds_dwordx4 v[180:181], off
	s_waitcnt lgkmcnt(8)
	s_barrier
	s_waitcnt lgkmcnt(0)
	s_waitcnt lgkmcnt(0)
	v_mfma_f32_16x16x32_bf16 v[140:143], v[48:51], v[144:147], 0
	v_mfma_f32_16x16x32_bf16 v[136:139], v[56:59], v[144:147], 0
	v_mfma_f32_16x16x32_bf16 v[124:127], v[48:51], v[152:155], 0
	v_mfma_f32_16x16x32_bf16 v[120:123], v[56:59], v[152:155], 0
	v_mfma_f32_16x16x32_bf16 v[108:111], v[48:51], v[172:175], 0
	v_mfma_f32_16x16x32_bf16 v[104:107], v[56:59], v[172:175], 0
	v_mfma_f32_16x16x32_bf16 v[92:95], v[48:51], v[188:191], 0
	v_mfma_f32_16x16x32_bf16 v[88:91], v[56:59], v[188:191], 0
	v_mfma_f32_16x16x32_bf16 v[140:143], v[52:55], v[148:151], v[140:143]
	v_mfma_f32_16x16x32_bf16 v[136:139], v[60:63], v[148:151], v[136:139]
	v_mfma_f32_16x16x32_bf16 v[124:127], v[52:55], v[156:159], v[124:127]
	v_mfma_f32_16x16x32_bf16 v[120:123], v[60:63], v[156:159], v[120:123]
	v_mfma_f32_16x16x32_bf16 v[108:111], v[52:55], v[176:179], v[108:111]
	v_mfma_f32_16x16x32_bf16 v[104:107], v[60:63], v[176:179], v[104:107]
	v_mfma_f32_16x16x32_bf16 v[92:95], v[52:55], v[192:195], v[92:95]
	v_mfma_f32_16x16x32_bf16 v[88:91], v[60:63], v[192:195], v[88:91]
	s_barrier
	s_add_i32 s47, s19, s10
	v_lshl_add_u64 v[180:181], s[52:53], 0, v[160:161]
	s_mov_b32 m0, s47
	ds_read_b128 v[196:199], v187
	ds_read_b128 v[200:203], v187 offset:1024
	ds_read_b128 v[204:207], v187 offset:2048
	ds_read_b128 v[208:211], v187 offset:3072
	global_load_lds_dwordx4 v[180:181], off
	v_lshl_add_u64 v[212:213], s[52:53], 0, v[162:163]
	s_add_i32 m0, s47, 0x2000
	s_nop 0
	global_load_lds_dwordx4 v[212:213], off
	s_barrier
	s_waitcnt lgkmcnt(0)
	s_waitcnt lgkmcnt(0)
	v_mfma_f32_16x16x32_bf16 v[132:135], v[196:199], v[144:147], 0
	v_mfma_f32_16x16x32_bf16 v[128:131], v[204:207], v[144:147], 0
	v_mfma_f32_16x16x32_bf16 v[116:119], v[196:199], v[152:155], 0
	v_mfma_f32_16x16x32_bf16 v[112:115], v[204:207], v[152:155], 0
	v_mfma_f32_16x16x32_bf16 v[100:103], v[196:199], v[172:175], 0
	v_mfma_f32_16x16x32_bf16 v[96:99], v[204:207], v[172:175], 0
	v_mfma_f32_16x16x32_bf16 v[84:87], v[196:199], v[188:191], 0
	v_mfma_f32_16x16x32_bf16 v[80:83], v[204:207], v[188:191], 0
	v_mfma_f32_16x16x32_bf16 v[132:135], v[200:203], v[148:151], v[132:135]
	v_mfma_f32_16x16x32_bf16 v[128:131], v[208:211], v[148:151], v[128:131]
	v_mfma_f32_16x16x32_bf16 v[116:119], v[200:203], v[156:159], v[116:119]
	v_mfma_f32_16x16x32_bf16 v[112:115], v[208:211], v[156:159], v[112:115]
	v_mfma_f32_16x16x32_bf16 v[100:103], v[200:203], v[176:179], v[100:103]
	v_mfma_f32_16x16x32_bf16 v[96:99], v[208:211], v[176:179], v[96:99]
	v_mfma_f32_16x16x32_bf16 v[84:87], v[200:203], v[192:195], v[84:87]
	v_mfma_f32_16x16x32_bf16 v[80:83], v[208:211], v[192:195], v[80:83]
	s_mov_b32 m0, s11
	v_lshl_add_u64 v[214:215], s[54:55], 0, v[160:161]
	s_barrier
	ds_read_b128 v[144:147], v186 offset:16384
	ds_read_b128 v[148:151], v186 offset:17408
	ds_read_b128 v[152:155], v186 offset:18432
	ds_read_b128 v[156:159], v186 offset:19456
	ds_read_b128 v[172:175], v186 offset:20480
	ds_read_b128 v[176:179], v186 offset:21504
	ds_read_b128 v[188:191], v186 offset:22528
	ds_read_b128 v[192:195], v186 offset:23552
	global_load_lds_dwordx4 v[214:215], off
	v_lshl_add_u64 v[216:217], s[54:55], 0, v[162:163]
	s_mov_b32 m0, s12
	s_nop 0
	global_load_lds_dwordx4 v[216:217], off
	s_barrier
	s_waitcnt lgkmcnt(0)
	s_waitcnt lgkmcnt(0)
	v_mfma_f32_16x16x32_bf16 v[76:79], v[48:51], v[144:147], 0
	v_mfma_f32_16x16x32_bf16 v[72:75], v[56:59], v[144:147], 0
	v_mfma_f32_16x16x32_bf16 v[44:47], v[48:51], v[152:155], 0
	v_mfma_f32_16x16x32_bf16 v[40:43], v[56:59], v[152:155], 0
	v_mfma_f32_16x16x32_bf16 v[28:31], v[48:51], v[172:175], 0
	v_mfma_f32_16x16x32_bf16 v[24:27], v[56:59], v[172:175], 0
	v_mfma_f32_16x16x32_bf16 v[12:15], v[48:51], v[188:191], 0
	v_mfma_f32_16x16x32_bf16 v[8:11], v[56:59], v[188:191], 0
	v_mfma_f32_16x16x32_bf16 v[76:79], v[52:55], v[148:151], v[76:79]
	v_mfma_f32_16x16x32_bf16 v[72:75], v[60:63], v[148:151], v[72:75]
	v_mfma_f32_16x16x32_bf16 v[44:47], v[52:55], v[156:159], v[44:47]
	v_mfma_f32_16x16x32_bf16 v[40:43], v[60:63], v[156:159], v[40:43]
	v_mfma_f32_16x16x32_bf16 v[28:31], v[52:55], v[176:179], v[28:31]
	v_mfma_f32_16x16x32_bf16 v[24:27], v[60:63], v[176:179], v[24:27]
	v_mfma_f32_16x16x32_bf16 v[12:15], v[52:55], v[192:195], v[12:15]
	v_mfma_f32_16x16x32_bf16 v[8:11], v[60:63], v[192:195], v[8:11]
	s_barrier
	s_add_u32 s50, s52, 0x40000
	s_addc_u32 s51, s53, 0
	s_add_i32 s47, s20, s10
	v_lshl_add_u64 v[48:49], s[50:51], 0, v[160:161]
	s_mov_b32 m0, s47
	s_nop 0
	global_load_lds_dwordx4 v[48:49], off
	v_lshl_add_u64 v[48:49], s[50:51], 0, v[162:163]
	s_add_i32 m0, s47, 0x2000
	s_nop 0
	global_load_lds_dwordx4 v[48:49], off
	s_waitcnt vmcnt(6)
	s_barrier
	v_mfma_f32_16x16x32_bf16 v[36:39], v[196:199], v[152:155], 0
	v_mfma_f32_16x16x32_bf16 v[32:35], v[204:207], v[152:155], 0
	v_mfma_f32_16x16x32_bf16 v[20:23], v[196:199], v[172:175], 0
	v_mfma_f32_16x16x32_bf16 v[16:19], v[204:207], v[172:175], 0
	v_mfma_f32_16x16x32_bf16 v[4:7], v[196:199], v[188:191], 0
	v_mfma_f32_16x16x32_bf16 v[0:3], v[204:207], v[188:191], 0
	v_mfma_f32_16x16x32_bf16 v[48:51], v[196:199], v[144:147], 0
	v_mfma_f32_16x16x32_bf16 v[52:55], v[204:207], v[144:147], 0
	v_mfma_f32_16x16x32_bf16 v[36:39], v[200:203], v[156:159], v[36:39]
	v_mfma_f32_16x16x32_bf16 v[32:35], v[208:211], v[156:159], v[32:35]
	v_mfma_f32_16x16x32_bf16 v[20:23], v[200:203], v[176:179], v[20:23]
	v_mfma_f32_16x16x32_bf16 v[16:19], v[208:211], v[176:179], v[16:19]
	v_mfma_f32_16x16x32_bf16 v[4:7], v[200:203], v[192:195], v[4:7]
	v_mfma_f32_16x16x32_bf16 v[0:3], v[208:211], v[192:195], v[0:3]
	v_mfma_f32_16x16x32_bf16 v[48:51], v[200:203], v[148:151], v[48:51]
	v_mfma_f32_16x16x32_bf16 v[52:55], v[208:211], v[148:151], v[52:55]
	s_add_i32 s47, 0, 0x18000
	v_add_u32_e32 v68, s47, v183
	s_barrier
	ds_read_b128 v[56:59], v68
	ds_read_b128 v[60:63], v68 offset:1024
	ds_read_b128 v[64:67], v68 offset:2048
	ds_read_b128 v[68:71], v68 offset:3072
	s_add_u32 s50, s54, 0x40000
	s_addc_u32 s51, s55, 0
	s_mov_b32 m0, s13
	v_lshl_add_u64 v[196:197], s[50:51], 0, v[160:161]
	ds_read_b128 v[144:147], v186 offset:32768
	ds_read_b128 v[148:151], v186 offset:33792
	ds_read_b128 v[152:155], v186 offset:34816
	ds_read_b128 v[156:159], v186 offset:35840
	ds_read_b128 v[172:175], v186 offset:36864
	ds_read_b128 v[176:179], v186 offset:37888
	ds_read_b128 v[188:191], v186 offset:38912
	ds_read_b128 v[192:195], v186 offset:39936
	global_load_lds_dwordx4 v[196:197], off
	v_lshl_add_u64 v[196:197], s[50:51], 0, v[162:163]
	s_mov_b32 m0, s14
	s_nop 0
	global_load_lds_dwordx4 v[196:197], off
	s_waitcnt lgkmcnt(8)
	s_barrier
	s_waitcnt lgkmcnt(0)
	s_waitcnt lgkmcnt(0)
	v_mfma_f32_16x16x32_bf16 v[140:143], v[56:59], v[144:147], v[140:143]
	v_mfma_f32_16x16x32_bf16 v[136:139], v[64:67], v[144:147], v[136:139]
	v_mfma_f32_16x16x32_bf16 v[124:127], v[56:59], v[152:155], v[124:127]
	v_mfma_f32_16x16x32_bf16 v[120:123], v[64:67], v[152:155], v[120:123]
	v_mfma_f32_16x16x32_bf16 v[108:111], v[56:59], v[172:175], v[108:111]
	v_mfma_f32_16x16x32_bf16 v[104:107], v[64:67], v[172:175], v[104:107]
	v_mfma_f32_16x16x32_bf16 v[92:95], v[56:59], v[188:191], v[92:95]
	v_mfma_f32_16x16x32_bf16 v[88:91], v[64:67], v[188:191], v[88:91]
	v_mfma_f32_16x16x32_bf16 v[140:143], v[60:63], v[148:151], v[140:143]
	v_mfma_f32_16x16x32_bf16 v[136:139], v[68:71], v[148:151], v[136:139]
	v_mfma_f32_16x16x32_bf16 v[124:127], v[60:63], v[156:159], v[124:127]
	v_mfma_f32_16x16x32_bf16 v[120:123], v[68:71], v[156:159], v[120:123]
	v_mfma_f32_16x16x32_bf16 v[108:111], v[60:63], v[176:179], v[108:111]
	v_mfma_f32_16x16x32_bf16 v[104:107], v[68:71], v[176:179], v[104:107]
	v_mfma_f32_16x16x32_bf16 v[92:95], v[60:63], v[192:195], v[92:95]
	v_mfma_f32_16x16x32_bf16 v[88:91], v[68:71], v[192:195], v[88:91]
	s_barrier
	s_add_i32 s54, 0, 0x1c000
	s_add_i32 s47, s47, s10
	v_add_u32_e32 v208, s54, v183
	v_lshl_add_u64 v[180:181], v[180:181], 0, s[28:29]
	s_mov_b32 m0, s47
	ds_read_b128 v[196:199], v208
	ds_read_b128 v[200:203], v208 offset:1024
	ds_read_b128 v[204:207], v208 offset:2048
	ds_read_b128 v[208:211], v208 offset:3072
	global_load_lds_dwordx4 v[180:181], off
	v_lshl_add_u64 v[180:181], v[212:213], 0, s[28:29]
	s_add_i32 m0, s47, 0x2000
	s_nop 0
	global_load_lds_dwordx4 v[180:181], off
	s_barrier
	s_waitcnt lgkmcnt(0)
	s_waitcnt lgkmcnt(0)
	v_mfma_f32_16x16x32_bf16 v[132:135], v[196:199], v[144:147], v[132:135]
	v_mfma_f32_16x16x32_bf16 v[128:131], v[204:207], v[144:147], v[128:131]
	v_mfma_f32_16x16x32_bf16 v[116:119], v[196:199], v[152:155], v[116:119]
	v_mfma_f32_16x16x32_bf16 v[112:115], v[204:207], v[152:155], v[112:115]
	v_mfma_f32_16x16x32_bf16 v[100:103], v[196:199], v[172:175], v[100:103]
	v_mfma_f32_16x16x32_bf16 v[96:99], v[204:207], v[172:175], v[96:99]
	v_mfma_f32_16x16x32_bf16 v[84:87], v[196:199], v[188:191], v[84:87]
	v_mfma_f32_16x16x32_bf16 v[80:83], v[204:207], v[188:191], v[80:83]
	v_mfma_f32_16x16x32_bf16 v[132:135], v[200:203], v[148:151], v[132:135]
	v_mfma_f32_16x16x32_bf16 v[128:131], v[208:211], v[148:151], v[128:131]
	v_mfma_f32_16x16x32_bf16 v[116:119], v[200:203], v[156:159], v[116:119]
	v_mfma_f32_16x16x32_bf16 v[112:115], v[208:211], v[156:159], v[112:115]
	v_mfma_f32_16x16x32_bf16 v[100:103], v[200:203], v[176:179], v[100:103]
	v_mfma_f32_16x16x32_bf16 v[96:99], v[208:211], v[176:179], v[96:99]
	v_mfma_f32_16x16x32_bf16 v[84:87], v[200:203], v[192:195], v[84:87]
	v_mfma_f32_16x16x32_bf16 v[80:83], v[208:211], v[192:195], v[80:83]
	s_mov_b32 m0, s16
	v_lshl_add_u64 v[180:181], v[214:215], 0, s[28:29]
	s_barrier
	ds_read_b128 v[144:147], v186 offset:49152
	ds_read_b128 v[148:151], v186 offset:50176
	ds_read_b128 v[152:155], v186 offset:51200
	ds_read_b128 v[156:159], v186 offset:52224
	ds_read_b128 v[172:175], v186 offset:53248
	ds_read_b128 v[176:179], v186 offset:54272
	ds_read_b128 v[188:191], v186 offset:55296
	ds_read_b128 v[192:195], v186 offset:56320
	global_load_lds_dwordx4 v[180:181], off
	v_lshl_add_u64 v[180:181], v[216:217], 0, s[28:29]
	s_mov_b32 m0, s17
	s_nop 0
	global_load_lds_dwordx4 v[180:181], off
	s_barrier
	s_waitcnt lgkmcnt(0)
	s_waitcnt lgkmcnt(0)
	v_mfma_f32_16x16x32_bf16 v[76:79], v[56:59], v[144:147], v[76:79]
	v_mfma_f32_16x16x32_bf16 v[72:75], v[64:67], v[144:147], v[72:75]
	v_mfma_f32_16x16x32_bf16 v[44:47], v[56:59], v[152:155], v[44:47]
	v_mfma_f32_16x16x32_bf16 v[40:43], v[64:67], v[152:155], v[40:43]
	v_mfma_f32_16x16x32_bf16 v[28:31], v[56:59], v[172:175], v[28:31]
	v_mfma_f32_16x16x32_bf16 v[24:27], v[64:67], v[172:175], v[24:27]
	v_mfma_f32_16x16x32_bf16 v[12:15], v[56:59], v[188:191], v[12:15]
	v_mfma_f32_16x16x32_bf16 v[8:11], v[64:67], v[188:191], v[8:11]
	v_mfma_f32_16x16x32_bf16 v[76:79], v[60:63], v[148:151], v[76:79]
	v_mfma_f32_16x16x32_bf16 v[72:75], v[68:71], v[148:151], v[72:75]
	v_mfma_f32_16x16x32_bf16 v[44:47], v[60:63], v[156:159], v[44:47]
	v_mfma_f32_16x16x32_bf16 v[40:43], v[68:71], v[156:159], v[40:43]
	v_mfma_f32_16x16x32_bf16 v[28:31], v[60:63], v[176:179], v[28:31]
	v_mfma_f32_16x16x32_bf16 v[24:27], v[68:71], v[176:179], v[24:27]
	v_mfma_f32_16x16x32_bf16 v[12:15], v[60:63], v[192:195], v[12:15]
	v_mfma_f32_16x16x32_bf16 v[8:11], v[68:71], v[192:195], v[8:11]
	s_barrier
	s_add_u32 s50, s52, 0x40080
	s_addc_u32 s51, s53, 0
	s_add_i32 s47, s54, s10
	v_lshl_add_u64 v[56:57], s[50:51], 0, v[160:161]
	s_mov_b32 m0, s47
	s_nop 0
	global_load_lds_dwordx4 v[56:57], off
	v_lshl_add_u64 v[56:57], s[50:51], 0, v[162:163]
	s_add_i32 m0, s47, 0x2000
	s_nop 0
	global_load_lds_dwordx4 v[56:57], off
	s_waitcnt vmcnt(6)
	s_barrier
	v_mfma_f32_16x16x32_bf16 v[48:51], v[196:199], v[144:147], v[48:51]
	v_mfma_f32_16x16x32_bf16 v[68:71], v[200:203], v[148:151], v[48:51]
	v_mfma_f32_16x16x32_bf16 v[48:51], v[204:207], v[144:147], v[52:55]
	v_mfma_f32_16x16x32_bf16 v[36:39], v[196:199], v[152:155], v[36:39]
	v_mfma_f32_16x16x32_bf16 v[32:35], v[204:207], v[152:155], v[32:35]
	v_mfma_f32_16x16x32_bf16 v[20:23], v[196:199], v[172:175], v[20:23]
	v_mfma_f32_16x16x32_bf16 v[16:19], v[204:207], v[172:175], v[16:19]
	v_mfma_f32_16x16x32_bf16 v[4:7], v[196:199], v[188:191], v[4:7]
	v_mfma_f32_16x16x32_bf16 v[0:3], v[204:207], v[188:191], v[0:3]
	v_mfma_f32_16x16x32_bf16 v[64:67], v[208:211], v[148:151], v[48:51]
	v_mfma_f32_16x16x32_bf16 v[36:39], v[200:203], v[156:159], v[36:39]
	v_mfma_f32_16x16x32_bf16 v[32:35], v[208:211], v[156:159], v[32:35]
	v_mfma_f32_16x16x32_bf16 v[20:23], v[200:203], v[176:179], v[20:23]
	v_mfma_f32_16x16x32_bf16 v[16:19], v[208:211], v[176:179], v[16:19]
	v_mfma_f32_16x16x32_bf16 v[4:7], v[200:203], v[192:195], v[4:7]
	v_mfma_f32_16x16x32_bf16 v[0:3], v[208:211], v[192:195], v[0:3]
	s_add_i32 s35, s35, 2
	s_add_u32 s48, s48, 0x100
	s_addc_u32 s49, s49, 0
	s_add_u32 s31, s31, 0x100
	s_addc_u32 s33, s33, 0
	s_cmp_gt_u32 s35, 13
	s_barrier

.LBB0_698:
	v_readlane_b32 s20, v254, 1
	v_readlane_b32 s21, v254, 2
	v_readlane_b32 s22, v254, 3
	v_readlane_b32 s23, v254, 4
	v_readlane_b32 s24, v254, 5
	v_readlane_b32 s25, v254, 6
	v_readlane_b32 s26, v254, 7
	v_readlane_b32 s27, v254, 8
	s_mov_b64 s[20:21], s[24:25]
	s_add_u32 s96, s20, 0x2c00
	s_addc_u32 s97, s21, 0
	s_add_u32 s86, s20, 0x5800
	s_addc_u32 s87, s21, 0
	s_add_u32 s28, s2, 0x21c00000
	s_addc_u32 s29, s3, 0
	s_add_u32 s30, s2, 0x14000000
	v_lshrrev_b32_e32 v16, 1, v8
	s_addc_u32 s31, s3, 0
	v_and_b32_e32 v16, 24, v16
	s_add_u32 s34, s2, 0x12000000
	v_and_b32_e32 v15, 15, v8
	v_lshlrev_b32_e32 v17, 1, v16
	v_lshlrev_b32_e32 v18, 2, v8
	s_addc_u32 s35, s3, 0
	v_lshl_or_b32 v17, v15, 6, v17
	s_lshl_b32 s2, s10, 13
	v_and_b32_e32 v18, 32, v18
	v_bitop3_b32 v19, v17, s2, v18 bitop3:0xde
	s_lshl_b32 s2, s17, 5
	s_mov_b64 s[52:53], 0x80
	s_and_b32 s20, s2, 0x60
	s_add_i32 m0, s12, 0x18000
	v_lshl_add_u64 v[6:7], v[6:7], 0, s[52:53]
	s_lshl_b32 s2, s20, 7
	s_waitcnt vmcnt(4)
	s_barrier
	global_load_lds_dwordx4 v[6:7], off
	v_lshl_add_u64 v[4:5], v[4:5], 0, s[52:53]
	s_add_i32 m0, s12, 0x1a000
	s_add_i32 s17, s12, 0x8000
	s_add_i32 s18, s12, 0xa000
	v_bitop3_b32 v232, v17, s2, v18 bitop3:0xde
	global_load_lds_dwordx4 v[4:5], off
	v_lshl_add_u64 v[2:3], v[2:3], 0, s[52:53]
	s_mov_b32 m0, s17
	s_add_u32 s2, s0, 0x40080
	global_load_lds_dwordx4 v[2:3], off
	v_lshl_add_u64 v[0:1], v[0:1], 0, s[52:53]
	s_mov_b32 m0, s18
	s_addc_u32 s3, s1, 0
	global_load_lds_dwordx4 v[0:1], off
	s_add_i32 m0, s12, 0x1c000
	v_lshl_add_u64 v[0:1], s[2:3], 0, v[160:161]
	global_load_lds_dwordx4 v[0:1], off
	v_lshl_add_u64 v[0:1], s[2:3], 0, v[162:163]
	s_add_i32 m0, s12, 0x1e000
	v_cmp_eq_u32_e64 s[38:39], 15, v15
	global_load_lds_dwordx4 v[0:1], off
	s_nop 0
	v_cndmask_b32_e64 v0, -1, 3, s[38:39]
	v_cmp_ne_u32_e32 vcc, 14, v15
	v_cmp_eq_u32_e64 s[42:43], 0, v15
	v_and_b32_e32 v1, 1, v9
	v_cndmask_b32_e32 v233, 2, v0, vcc
	v_cmp_eq_u32_e32 vcc, 1, v15
	s_waitcnt vmcnt(6)
	v_or_b32_e32 v235, s20, v16
	s_add_i32 s20, 0, 0x10000
	v_cndmask_b32_e64 v0, -1, 1, vcc
	v_cndmask_b32_e64 v234, v0, 0, s[42:43]
	v_and_b32_e32 v0, 14, v8
	v_cmp_eq_u32_e64 s[74:75], 14, v0
	v_lshlrev_b32_e32 v0, 14, v9
	v_and_b32_e32 v0, 0xffff8000, v0
	v_lshl_add_u32 v0, v10, 11, v0
	v_lshl_or_b32 v0, v1, 6, v0
	v_lshl_add_u32 v166, v11, 1, v0
	v_lshlrev_b32_e32 v0, 14, v12
	v_and_b32_e32 v0, 0xffff8000, v0
	v_lshl_add_u32 v0, v13, 11, v0
	v_and_b32_e32 v1, 1, v12
	v_lshl_or_b32 v0, v1, 6, v0
	s_add_i32 s21, 0, 0x14000
	v_lshl_or_b32 v231, s10, 6, v15
	v_cmp_ne_u32_e64 s[36:37], 15, v15
	v_cmp_ne_u32_e64 s[40:41], 0, v15
	v_cmp_gt_u32_e64 s[70:71], 2, v15
	s_ashr_i32 s19, s4, 31
	v_mov_b32_e32 v167, v165
	v_lshl_add_u32 v168, v14, 1, v0
	v_mov_b32_e32 v169, v165
	v_mov_b64_e32 v[170:171], 0x1600
	v_mov_b64_e32 v[172:173], 0x15ff
	v_add_u32_e32 v236, s20, v232
	v_add_u32_e32 v237, 0, v19
	v_add_u32_e32 v238, s21, v232
	v_mov_b32_e32 v239, 0x358637bd
	s_mov_b32 s33, 0x800000
	s_movk_i32 s65, 0xb00
	s_mov_b32 s54, 0xbf38aa3b
	s_mov_b32 s56, 0x3e6d3388
	s_mov_b32 s58, 0x3f07dc22
	s_mov_b32 s64, 0xbf3a00e3
	s_mov_b32 s66, 0x3f35f0e3
	s_mov_b32 s68, 0xbe11a98e
	s_mov_b32 s72, 0x3e027906
	s_mov_b64 s[22:23], s[26:27]
	s_barrier
	s_branch .LBB0_700
	s_nop 0
	s_nop 0
	s_nop 0
	s_nop 0
.LBB0_699:
	s_or_b64 exec, exec, s[0:1]
	s_and_b64 vcc, exec, s[76:77]
	s_mov_b32 s88, s2
	s_mov_b32 s84, s62
	s_mov_b64 s[0:1], s[24:25]
	s_mov_b64 s[90:91], s[26:27]
	s_cmpk_gt_u32 s5, 0xff
	s_cbranch_scc0 .Lepi1_ffnin
	s_barrier

.LBB0_702:
	s_ashr_i32 s63, s62, 31
	s_lshl_b64 s[22:23], s[62:63], 19
	s_add_u32 s26, s6, s22
	v_cmp_lt_i64_e32 vcc, s[24:25], v[170:171]
	s_addc_u32 s27, s7, s23
	s_and_b64 s[22:23], vcc, exec
	s_cselect_b32 s22, s27, s91
	s_cselect_b32 s23, s26, s90
	s_ashr_i32 s3, s2, 31
	s_lshl_b64 s[24:25], s[2:3], 19
	s_add_u32 s24, s8, s24
	s_addc_u32 s25, s9, s25
	s_and_b64 s[60:61], vcc, exec
	s_cselect_b32 s3, s25, s1
	s_cselect_b32 s51, s24, s0
	s_add_u32 vcc_lo, s90, 0x40080
	s_addc_u32 vcc_hi, s91, 0
	s_add_u32 s55, s0, 0x100
	s_addc_u32 s57, s1, 0
	s_mov_b32 s59, -2
	ds_read_b128 v[44:47], v236
	ds_read_b128 v[48:51], v236 offset:1024
	ds_read_b128 v[52:55], v236 offset:2048
	ds_read_b128 v[56:59], v236 offset:3072
	s_add_u32 s0, vcc_lo, 0xfffc0080
	s_addc_u32 s1, vcc_hi, -1
	s_cmp_eq_u32 s59, 12
	s_cselect_b32 s91, s22, s1
	s_cselect_b32 s90, s23, s0
	s_cselect_b32 s1, s3, s57
	s_cselect_b32 s0, s51, s55
	v_lshl_add_u64 v[190:191], vcc, 0, v[166:167]
	s_add_i32 m0, s12, 0xc000
	ds_read_b128 v[68:71], v237
	ds_read_b128 v[72:75], v237 offset:1024
	ds_read_b128 v[76:79], v237 offset:2048
	ds_read_b128 v[80:83], v237 offset:3072
	ds_read_b128 v[174:177], v237 offset:4096
	ds_read_b128 v[178:181], v237 offset:5120
	ds_read_b128 v[182:185], v237 offset:6144
	ds_read_b128 v[186:189], v237 offset:7168
	global_load_lds_dwordx4 v[190:191], off
	v_lshl_add_u64 v[190:191], vcc, 0, v[168:169]
	s_add_i32 m0, s12, 0xe000
	s_nop 0
	global_load_lds_dwordx4 v[190:191], off
	s_waitcnt lgkmcnt(8)
	s_barrier
	s_waitcnt lgkmcnt(0)
	s_waitcnt lgkmcnt(0)
	v_mfma_f32_16x16x32_bf16 v[156:159], v[44:47], v[68:71], 0
	v_mfma_f32_16x16x32_bf16 v[132:135], v[52:55], v[68:71], 0
	v_mfma_f32_16x16x32_bf16 v[152:155], v[44:47], v[76:79], 0
	v_mfma_f32_16x16x32_bf16 v[128:131], v[52:55], v[76:79], 0
	v_mfma_f32_16x16x32_bf16 v[140:143], v[44:47], v[174:177], 0
	v_mfma_f32_16x16x32_bf16 v[104:107], v[52:55], v[174:177], 0
	v_mfma_f32_16x16x32_bf16 v[144:147], v[44:47], v[182:185], 0
	v_mfma_f32_16x16x32_bf16 v[108:111], v[52:55], v[182:185], 0
	v_mfma_f32_16x16x32_bf16 v[156:159], v[48:51], v[72:75], v[156:159]
	v_mfma_f32_16x16x32_bf16 v[132:135], v[56:59], v[72:75], v[132:135]
	v_mfma_f32_16x16x32_bf16 v[152:155], v[48:51], v[80:83], v[152:155]
	v_mfma_f32_16x16x32_bf16 v[128:131], v[56:59], v[80:83], v[128:131]
	v_mfma_f32_16x16x32_bf16 v[140:143], v[48:51], v[178:181], v[140:143]
	v_mfma_f32_16x16x32_bf16 v[104:107], v[56:59], v[178:181], v[104:107]
	v_mfma_f32_16x16x32_bf16 v[144:147], v[48:51], v[186:189], v[144:147]
	v_mfma_f32_16x16x32_bf16 v[108:111], v[56:59], v[186:189], v[108:111]
	s_barrier
	s_add_i32 s60, s20, s11
	v_lshl_add_u64 v[214:215], s[0:1], 0, v[160:161]
	s_mov_b32 m0, s60
	ds_read_b128 v[190:193], v238
	ds_read_b128 v[194:197], v238 offset:1024
	ds_read_b128 v[198:201], v238 offset:2048
	ds_read_b128 v[202:205], v238 offset:3072
	global_load_lds_dwordx4 v[214:215], off
	v_lshl_add_u64 v[216:217], s[0:1], 0, v[162:163]
	s_add_i32 m0, s60, 0x2000
	s_nop 0
	global_load_lds_dwordx4 v[216:217], off
	s_barrier
	s_waitcnt lgkmcnt(0)
	s_waitcnt lgkmcnt(0)
	v_mfma_f32_16x16x32_bf16 v[148:151], v[190:193], v[68:71], 0
	v_mfma_f32_16x16x32_bf16 v[68:71], v[198:201], v[68:71], 0
	v_mfma_f32_16x16x32_bf16 v[148:151], v[194:197], v[72:75], v[148:151]
	v_mfma_f32_16x16x32_bf16 v[68:71], v[202:205], v[72:75], v[68:71]
	v_mfma_f32_16x16x32_bf16 v[72:75], v[190:193], v[76:79], 0
	v_mfma_f32_16x16x32_bf16 v[76:79], v[198:201], v[76:79], 0
	v_mfma_f32_16x16x32_bf16 v[100:103], v[198:201], v[174:177], 0
	v_mfma_f32_16x16x32_bf16 v[112:115], v[190:193], v[182:185], 0
	v_mfma_f32_16x16x32_bf16 v[96:99], v[198:201], v[182:185], 0
	v_mfma_f32_16x16x32_bf16 v[72:75], v[194:197], v[80:83], v[72:75]
	v_mfma_f32_16x16x32_bf16 v[76:79], v[202:205], v[80:83], v[76:79]
	v_mfma_f32_16x16x32_bf16 v[80:83], v[190:193], v[174:177], 0
	v_mfma_f32_16x16x32_bf16 v[100:103], v[202:205], v[178:181], v[100:103]
	v_mfma_f32_16x16x32_bf16 v[136:139], v[194:197], v[186:189], v[112:115]
	v_mfma_f32_16x16x32_bf16 v[96:99], v[202:205], v[186:189], v[96:99]
	v_mfma_f32_16x16x32_bf16 v[80:83], v[194:197], v[178:181], v[80:83]
	s_mov_b32 m0, s12
	v_lshl_add_u64 v[218:219], s[90:91], 0, v[160:161]
	s_barrier
	ds_read_b128 v[112:115], v237 offset:16384
	ds_read_b128 v[116:119], v237 offset:17408
	ds_read_b128 v[120:123], v237 offset:18432
	ds_read_b128 v[124:127], v237 offset:19456
	ds_read_b128 v[174:177], v237 offset:20480
	ds_read_b128 v[178:181], v237 offset:21504
	ds_read_b128 v[182:185], v237 offset:22528
	ds_read_b128 v[186:189], v237 offset:23552
	global_load_lds_dwordx4 v[218:219], off
	v_lshl_add_u64 v[220:221], s[90:91], 0, v[162:163]
	s_mov_b32 m0, s13
	s_nop 0
	global_load_lds_dwordx4 v[220:221], off
	s_barrier
	s_waitcnt lgkmcnt(0)
	s_waitcnt lgkmcnt(0)
	v_mfma_f32_16x16x32_bf16 v[92:95], v[44:47], v[112:115], 0
	v_mfma_f32_16x16x32_bf16 v[40:43], v[52:55], v[112:115], 0
	v_mfma_f32_16x16x32_bf16 v[88:91], v[44:47], v[120:123], 0
	v_mfma_f32_16x16x32_bf16 v[36:39], v[52:55], v[120:123], 0
	v_mfma_f32_16x16x32_bf16 v[60:63], v[44:47], v[174:177], 0
	v_mfma_f32_16x16x32_bf16 v[8:11], v[52:55], v[174:177], 0
	v_mfma_f32_16x16x32_bf16 v[16:19], v[52:55], v[182:185], 0
	v_mfma_f32_16x16x32_bf16 v[92:95], v[48:51], v[116:119], v[92:95]
	v_mfma_f32_16x16x32_bf16 v[40:43], v[56:59], v[116:119], v[40:43]
	v_mfma_f32_16x16x32_bf16 v[88:91], v[48:51], v[124:127], v[88:91]
	v_mfma_f32_16x16x32_bf16 v[36:39], v[56:59], v[124:127], v[36:39]
	v_mfma_f32_16x16x32_bf16 v[60:63], v[48:51], v[178:181], v[60:63]
	v_mfma_f32_16x16x32_bf16 v[8:11], v[56:59], v[178:181], v[8:11]
	v_mfma_f32_16x16x32_bf16 v[44:47], v[44:47], v[182:185], 0
	v_mfma_f32_16x16x32_bf16 v[16:19], v[56:59], v[186:189], v[16:19]
	v_mfma_f32_16x16x32_bf16 v[44:47], v[48:51], v[186:189], v[44:47]
	s_barrier
	s_add_u32 s60, s0, 0x40000
	s_addc_u32 s61, s1, 0
	s_add_i32 s63, s21, s11
	v_lshl_add_u64 v[48:49], s[60:61], 0, v[160:161]
	s_mov_b32 m0, s63
	s_nop 0
	global_load_lds_dwordx4 v[48:49], off
	v_lshl_add_u64 v[48:49], s[60:61], 0, v[162:163]
	s_add_i32 m0, s63, 0x2000
	s_nop 0
	global_load_lds_dwordx4 v[48:49], off
	s_waitcnt vmcnt(6)
	s_barrier
	v_mfma_f32_16x16x32_bf16 v[28:31], v[198:201], v[112:115], 0
	v_mfma_f32_16x16x32_bf16 v[24:27], v[190:193], v[120:123], 0
	v_mfma_f32_16x16x32_bf16 v[12:15], v[198:201], v[120:123], 0
	v_mfma_f32_16x16x32_bf16 v[20:23], v[190:193], v[174:177], 0
	v_mfma_f32_16x16x32_bf16 v[4:7], v[198:201], v[174:177], 0
	v_mfma_f32_16x16x32_bf16 v[32:35], v[190:193], v[182:185], 0
	v_mfma_f32_16x16x32_bf16 v[0:3], v[198:201], v[182:185], 0
	v_mfma_f32_16x16x32_bf16 v[48:51], v[190:193], v[112:115], 0
	v_mfma_f32_16x16x32_bf16 v[28:31], v[202:205], v[116:119], v[28:31]
	v_mfma_f32_16x16x32_bf16 v[24:27], v[194:197], v[124:127], v[24:27]
	v_mfma_f32_16x16x32_bf16 v[12:15], v[202:205], v[124:127], v[12:15]
	v_mfma_f32_16x16x32_bf16 v[20:23], v[194:197], v[178:181], v[20:23]
	v_mfma_f32_16x16x32_bf16 v[4:7], v[202:205], v[178:181], v[4:7]
	v_mfma_f32_16x16x32_bf16 v[32:35], v[194:197], v[186:189], v[32:35]
	v_mfma_f32_16x16x32_bf16 v[0:3], v[202:205], v[186:189], v[0:3]
	v_mfma_f32_16x16x32_bf16 v[48:51], v[194:197], v[116:119], v[48:51]
	s_add_i32 s63, 0, 0x18000
	v_add_u32_e32 v64, s63, v232
	s_barrier
	ds_read_b128 v[52:55], v64
	ds_read_b128 v[56:59], v64 offset:1024
	ds_read_b128 v[84:87], v64 offset:2048
	ds_read_b128 v[174:177], v64 offset:3072
	s_add_u32 s60, s90, 0x40000
	s_addc_u32 s61, s91, 0
	s_mov_b32 m0, s14
	v_lshl_add_u64 v[120:121], s[60:61], 0, v[160:161]
	ds_read_b128 v[64:67], v237 offset:32768
	ds_read_b128 v[112:115], v237 offset:33792
	ds_read_b128 v[116:119], v237 offset:34816
	ds_read_b128 v[178:181], v237 offset:35840
	ds_read_b128 v[182:185], v237 offset:36864
	ds_read_b128 v[186:189], v237 offset:37888
	ds_read_b128 v[190:193], v237 offset:38912
	ds_read_b128 v[194:197], v237 offset:39936
	global_load_lds_dwordx4 v[120:121], off
	v_lshl_add_u64 v[120:121], s[60:61], 0, v[162:163]
	s_mov_b32 m0, s15
	s_nop 0
	global_load_lds_dwordx4 v[120:121], off
	s_waitcnt lgkmcnt(8)
	s_barrier
	s_waitcnt lgkmcnt(0)
	s_waitcnt lgkmcnt(0)
	v_mfma_f32_16x16x32_bf16 v[120:123], v[52:55], v[64:67], v[156:159]
	v_mfma_f32_16x16x32_bf16 v[156:159], v[56:59], v[112:115], v[120:123]
	v_mfma_f32_16x16x32_bf16 v[120:123], v[84:87], v[64:67], v[132:135]
	v_mfma_f32_16x16x32_bf16 v[132:135], v[174:177], v[112:115], v[120:123]
	v_mfma_f32_16x16x32_bf16 v[120:123], v[52:55], v[116:119], v[152:155]
	v_mfma_f32_16x16x32_bf16 v[152:155], v[56:59], v[178:181], v[120:123]
	v_mfma_f32_16x16x32_bf16 v[120:123], v[84:87], v[116:119], v[128:131]
	v_mfma_f32_16x16x32_bf16 v[128:131], v[174:177], v[178:181], v[120:123]
	v_mfma_f32_16x16x32_bf16 v[120:123], v[52:55], v[182:185], v[140:143]
	v_mfma_f32_16x16x32_bf16 v[140:143], v[56:59], v[186:189], v[120:123]
	v_mfma_f32_16x16x32_bf16 v[104:107], v[84:87], v[182:185], v[104:107]
	v_mfma_f32_16x16x32_bf16 v[120:123], v[52:55], v[190:193], v[144:147]
	v_mfma_f32_16x16x32_bf16 v[108:111], v[84:87], v[190:193], v[108:111]
	v_mfma_f32_16x16x32_bf16 v[104:107], v[174:177], v[186:189], v[104:107]
	v_mfma_f32_16x16x32_bf16 v[144:147], v[56:59], v[194:197], v[120:123]
	v_mfma_f32_16x16x32_bf16 v[108:111], v[174:177], v[194:197], v[108:111]
	s_barrier
	s_add_i32 s60, 0, 0x1c000
	s_nop 0
	v_add_u32_e32 v120, s60, v232
	s_add_i32 s61, s63, s11
	ds_read_b128 v[198:201], v120
	ds_read_b128 v[202:205], v120 offset:1024
	ds_read_b128 v[206:209], v120 offset:2048
	ds_read_b128 v[210:213], v120 offset:3072
	v_lshl_add_u64 v[120:121], v[214:215], 0, s[52:53]
	s_mov_b32 m0, s61
	s_nop 0
	global_load_lds_dwordx4 v[120:121], off
	v_lshl_add_u64 v[120:121], v[216:217], 0, s[52:53]
	s_add_i32 m0, s61, 0x2000
	s_nop 0
	global_load_lds_dwordx4 v[120:121], off
	s_barrier
	s_waitcnt lgkmcnt(0)
	s_waitcnt lgkmcnt(0)
	v_mfma_f32_16x16x32_bf16 v[120:123], v[198:201], v[64:67], v[148:151]
	v_mfma_f32_16x16x32_bf16 v[64:67], v[206:209], v[64:67], v[68:71]
	v_mfma_f32_16x16x32_bf16 v[124:127], v[210:213], v[112:115], v[64:67]
	v_mfma_f32_16x16x32_bf16 v[64:67], v[198:201], v[116:119], v[72:75]
	v_mfma_f32_16x16x32_bf16 v[148:151], v[202:205], v[112:115], v[120:123]
	v_mfma_f32_16x16x32_bf16 v[120:123], v[202:205], v[178:181], v[64:67]
	v_mfma_f32_16x16x32_bf16 v[64:67], v[206:209], v[116:119], v[76:79]
	v_mfma_f32_16x16x32_bf16 v[112:115], v[210:213], v[178:181], v[64:67]
	v_mfma_f32_16x16x32_bf16 v[64:67], v[198:201], v[182:185], v[80:83]
	v_mfma_f32_16x16x32_bf16 v[116:119], v[202:205], v[186:189], v[64:67]
	v_mfma_f32_16x16x32_bf16 v[64:67], v[206:209], v[182:185], v[100:103]
	v_mfma_f32_16x16x32_bf16 v[100:103], v[210:213], v[186:189], v[64:67]
	v_mfma_f32_16x16x32_bf16 v[64:67], v[198:201], v[190:193], v[136:139]
	v_mfma_f32_16x16x32_bf16 v[136:139], v[202:205], v[194:197], v[64:67]
	v_mfma_f32_16x16x32_bf16 v[64:67], v[206:209], v[190:193], v[96:99]
	v_mfma_f32_16x16x32_bf16 v[96:99], v[210:213], v[194:197], v[64:67]
	s_mov_b32 m0, s17
	s_nop 4
	v_lshl_add_u64 v[64:65], v[218:219], 0, s[52:53]
	s_barrier
	ds_read_b128 v[68:71], v237 offset:49152
	ds_read_b128 v[72:75], v237 offset:50176
	ds_read_b128 v[76:79], v237 offset:51200
	ds_read_b128 v[80:83], v237 offset:52224
	ds_read_b128 v[178:181], v237 offset:53248
	ds_read_b128 v[182:185], v237 offset:54272
	ds_read_b128 v[186:189], v237 offset:55296
	ds_read_b128 v[190:193], v237 offset:56320
	global_load_lds_dwordx4 v[64:65], off
	v_lshl_add_u64 v[64:65], v[220:221], 0, s[52:53]
	s_mov_b32 m0, s18
	s_nop 0
	global_load_lds_dwordx4 v[64:65], off
	s_barrier
	s_waitcnt lgkmcnt(0)
	s_waitcnt lgkmcnt(0)
	v_mfma_f32_16x16x32_bf16 v[64:67], v[52:55], v[68:71], v[92:95]
	v_mfma_f32_16x16x32_bf16 v[92:95], v[56:59], v[72:75], v[64:67]
	v_mfma_f32_16x16x32_bf16 v[40:43], v[84:87], v[68:71], v[40:43]
	v_mfma_f32_16x16x32_bf16 v[64:67], v[52:55], v[76:79], v[88:91]
	v_mfma_f32_16x16x32_bf16 v[36:39], v[84:87], v[76:79], v[36:39]
	v_mfma_f32_16x16x32_bf16 v[60:63], v[52:55], v[178:181], v[60:63]
	v_mfma_f32_16x16x32_bf16 v[8:11], v[84:87], v[178:181], v[8:11]
	v_mfma_f32_16x16x32_bf16 v[44:47], v[52:55], v[186:189], v[44:47]
	v_mfma_f32_16x16x32_bf16 v[16:19], v[84:87], v[186:189], v[16:19]
	v_mfma_f32_16x16x32_bf16 v[40:43], v[174:177], v[72:75], v[40:43]
	v_mfma_f32_16x16x32_bf16 v[88:91], v[56:59], v[80:83], v[64:67]
	v_mfma_f32_16x16x32_bf16 v[36:39], v[174:177], v[80:83], v[36:39]
	v_mfma_f32_16x16x32_bf16 v[60:63], v[56:59], v[182:185], v[60:63]
	v_mfma_f32_16x16x32_bf16 v[8:11], v[174:177], v[182:185], v[8:11]
	v_mfma_f32_16x16x32_bf16 v[64:67], v[56:59], v[190:193], v[44:47]
	v_mfma_f32_16x16x32_bf16 v[16:19], v[174:177], v[190:193], v[16:19]
	s_barrier
	s_add_u32 s0, s0, 0x40080
	s_addc_u32 s1, s1, 0
	s_add_i32 s60, s60, s11
	v_lshl_add_u64 v[44:45], s[0:1], 0, v[160:161]
	s_mov_b32 m0, s60
	s_nop 0
	global_load_lds_dwordx4 v[44:45], off
	v_lshl_add_u64 v[44:45], s[0:1], 0, v[162:163]
	s_add_i32 m0, s60, 0x2000
	s_nop 0
	global_load_lds_dwordx4 v[44:45], off
	s_waitcnt vmcnt(6)
	s_barrier
	v_mfma_f32_16x16x32_bf16 v[44:47], v[198:201], v[68:71], v[48:51]
	v_mfma_f32_16x16x32_bf16 v[28:31], v[206:209], v[68:71], v[28:31]
	v_mfma_f32_16x16x32_bf16 v[24:27], v[198:201], v[76:79], v[24:27]
	v_mfma_f32_16x16x32_bf16 v[12:15], v[206:209], v[76:79], v[12:15]
	v_mfma_f32_16x16x32_bf16 v[20:23], v[198:201], v[178:181], v[20:23]
	v_mfma_f32_16x16x32_bf16 v[4:7], v[206:209], v[178:181], v[4:7]
	v_mfma_f32_16x16x32_bf16 v[32:35], v[198:201], v[186:189], v[32:35]
	v_mfma_f32_16x16x32_bf16 v[0:3], v[206:209], v[186:189], v[0:3]
	v_mfma_f32_16x16x32_bf16 v[84:87], v[202:205], v[72:75], v[44:47]
	v_mfma_f32_16x16x32_bf16 v[28:31], v[210:213], v[72:75], v[28:31]
	v_mfma_f32_16x16x32_bf16 v[24:27], v[202:205], v[80:83], v[24:27]
	v_mfma_f32_16x16x32_bf16 v[12:15], v[210:213], v[80:83], v[12:15]
	v_mfma_f32_16x16x32_bf16 v[20:23], v[202:205], v[182:185], v[20:23]
	v_mfma_f32_16x16x32_bf16 v[4:7], v[210:213], v[182:185], v[4:7]
	v_mfma_f32_16x16x32_bf16 v[32:35], v[202:205], v[190:193], v[32:35]
	v_mfma_f32_16x16x32_bf16 v[0:3], v[210:213], v[190:193], v[0:3]
	s_add_i32 s59, s59, 2
	s_add_u32 vcc_lo, vcc_lo, 0x100
	s_addc_u32 vcc_hi, vcc_hi, 0
	s_add_u32 s55, s55, 0x100
	s_addc_u32 s57, s57, 0
	s_cmp_gt_u32 s59, 13
	s_barrier

.LBB0_887:
	s_add_u32 s37, s10, 0x100
	s_addc_u32 s38, s11, 0
	s_mov_b32 s39, -2
	ds_read_b128 v[140:143], v149
	ds_read_b128 v[152:155], v149 offset:1024
	ds_read_b128 v[156:159], v149 offset:2048
	ds_read_b128 v[160:163], v149 offset:3072
	s_add_u32 s10, s2, 0x100
	s_addc_u32 s11, s3, 0
	s_cmp_eq_u32 s39, 40
	s_cselect_b32 s15, s7, s11
	s_cselect_b32 s14, s6, s10
	s_cselect_b32 s13, s5, s38
	s_cselect_b32 s12, s4, s37
	v_lshl_add_u64 v[144:145], s[2:3], 0, v[132:133]
	s_add_i32 m0, s23, 0xc000
	ds_read_b128 v[164:167], v150
	ds_read_b128 v[168:171], v150 offset:1024
	ds_read_b128 v[172:175], v150 offset:2048
	ds_read_b128 v[176:179], v150 offset:3072
	ds_read_b128 v[180:183], v150 offset:4096
	ds_read_b128 v[184:187], v150 offset:5120
	ds_read_b128 v[188:191], v150 offset:6144
	ds_read_b128 v[192:195], v150 offset:7168
	global_load_lds_dwordx4 v[144:145], off
	v_lshl_add_u64 v[144:145], s[2:3], 0, v[134:135]
	s_add_i32 m0, s23, 0xe000
	s_nop 0
	global_load_lds_dwordx4 v[144:145], off
	s_waitcnt lgkmcnt(8)
	s_barrier
	s_waitcnt lgkmcnt(0)
	s_waitcnt lgkmcnt(0)
	v_mfma_f32_16x16x32_bf16 v[124:127], v[140:143], v[164:167], 0
	v_mfma_f32_16x16x32_bf16 v[120:123], v[156:159], v[164:167], 0
	v_mfma_f32_16x16x32_bf16 v[116:119], v[140:143], v[172:175], 0
	v_mfma_f32_16x16x32_bf16 v[112:115], v[156:159], v[172:175], 0
	v_mfma_f32_16x16x32_bf16 v[92:95], v[140:143], v[180:183], 0
	v_mfma_f32_16x16x32_bf16 v[88:91], v[156:159], v[180:183], 0
	v_mfma_f32_16x16x32_bf16 v[84:87], v[140:143], v[188:191], 0
	v_mfma_f32_16x16x32_bf16 v[80:83], v[156:159], v[188:191], 0
	v_mfma_f32_16x16x32_bf16 v[124:127], v[152:155], v[168:171], v[124:127]
	v_mfma_f32_16x16x32_bf16 v[120:123], v[160:163], v[168:171], v[120:123]
	v_mfma_f32_16x16x32_bf16 v[116:119], v[152:155], v[176:179], v[116:119]
	v_mfma_f32_16x16x32_bf16 v[112:115], v[160:163], v[176:179], v[112:115]
	v_mfma_f32_16x16x32_bf16 v[92:95], v[152:155], v[184:187], v[92:95]
	v_mfma_f32_16x16x32_bf16 v[88:91], v[160:163], v[184:187], v[88:91]
	v_mfma_f32_16x16x32_bf16 v[84:87], v[152:155], v[192:195], v[84:87]
	v_mfma_f32_16x16x32_bf16 v[80:83], v[160:163], v[192:195], v[80:83]
	s_barrier
	s_add_i32 s2, s30, s22
	v_lshl_add_u64 v[144:145], s[12:13], 0, v[128:129]
	s_mov_b32 m0, s2
	ds_read_b128 v[196:199], v151
	ds_read_b128 v[200:203], v151 offset:1024
	ds_read_b128 v[204:207], v151 offset:2048
	ds_read_b128 v[208:211], v151 offset:3072
	global_load_lds_dwordx4 v[144:145], off
	v_lshl_add_u64 v[212:213], s[12:13], 0, v[130:131]
	s_add_i32 m0, s2, 0x2000
	s_nop 0
	global_load_lds_dwordx4 v[212:213], off
	s_barrier
	s_waitcnt lgkmcnt(0)
	s_waitcnt lgkmcnt(0)
	v_mfma_f32_16x16x32_bf16 v[108:111], v[196:199], v[164:167], 0
	v_mfma_f32_16x16x32_bf16 v[104:107], v[204:207], v[164:167], 0
	v_mfma_f32_16x16x32_bf16 v[100:103], v[196:199], v[172:175], 0
	v_mfma_f32_16x16x32_bf16 v[96:99], v[204:207], v[172:175], 0
	v_mfma_f32_16x16x32_bf16 v[76:79], v[196:199], v[180:183], 0
	v_mfma_f32_16x16x32_bf16 v[72:75], v[204:207], v[180:183], 0
	v_mfma_f32_16x16x32_bf16 v[68:71], v[196:199], v[188:191], 0
	v_mfma_f32_16x16x32_bf16 v[64:67], v[204:207], v[188:191], 0
	v_mfma_f32_16x16x32_bf16 v[108:111], v[200:203], v[168:171], v[108:111]
	v_mfma_f32_16x16x32_bf16 v[104:107], v[208:211], v[168:171], v[104:107]
	v_mfma_f32_16x16x32_bf16 v[100:103], v[200:203], v[176:179], v[100:103]
	v_mfma_f32_16x16x32_bf16 v[96:99], v[208:211], v[176:179], v[96:99]
	v_mfma_f32_16x16x32_bf16 v[76:79], v[200:203], v[184:187], v[76:79]
	v_mfma_f32_16x16x32_bf16 v[72:75], v[208:211], v[184:187], v[72:75]
	v_mfma_f32_16x16x32_bf16 v[68:71], v[200:203], v[192:195], v[68:71]
	v_mfma_f32_16x16x32_bf16 v[64:67], v[208:211], v[192:195], v[64:67]
	s_mov_b32 m0, s23
	v_lshl_add_u64 v[214:215], s[14:15], 0, v[128:129]
	s_barrier
	ds_read_b128 v[164:167], v150 offset:16384
	ds_read_b128 v[168:171], v150 offset:17408
	ds_read_b128 v[172:175], v150 offset:18432
	ds_read_b128 v[176:179], v150 offset:19456
	ds_read_b128 v[180:183], v150 offset:20480
	ds_read_b128 v[184:187], v150 offset:21504
	ds_read_b128 v[188:191], v150 offset:22528
	ds_read_b128 v[192:195], v150 offset:23552
	global_load_lds_dwordx4 v[214:215], off
	v_lshl_add_u64 v[216:217], s[14:15], 0, v[130:131]
	s_mov_b32 m0, s24
	s_nop 0
	global_load_lds_dwordx4 v[216:217], off
	s_barrier
	s_waitcnt lgkmcnt(0)
	s_waitcnt lgkmcnt(0)
	v_mfma_f32_16x16x32_bf16 v[60:63], v[140:143], v[164:167], 0
	v_mfma_f32_16x16x32_bf16 v[56:59], v[156:159], v[164:167], 0
	v_mfma_f32_16x16x32_bf16 v[52:55], v[140:143], v[172:175], 0
	v_mfma_f32_16x16x32_bf16 v[48:51], v[156:159], v[172:175], 0
	v_mfma_f32_16x16x32_bf16 v[28:31], v[140:143], v[180:183], 0
	v_mfma_f32_16x16x32_bf16 v[24:27], v[156:159], v[180:183], 0
	v_mfma_f32_16x16x32_bf16 v[16:19], v[140:143], v[188:191], 0
	v_mfma_f32_16x16x32_bf16 v[8:11], v[156:159], v[188:191], 0
	v_mfma_f32_16x16x32_bf16 v[60:63], v[152:155], v[168:171], v[60:63]
	v_mfma_f32_16x16x32_bf16 v[56:59], v[160:163], v[168:171], v[56:59]
	v_mfma_f32_16x16x32_bf16 v[52:55], v[152:155], v[176:179], v[52:55]
	v_mfma_f32_16x16x32_bf16 v[48:51], v[160:163], v[176:179], v[48:51]
	v_mfma_f32_16x16x32_bf16 v[28:31], v[152:155], v[184:187], v[28:31]
	v_mfma_f32_16x16x32_bf16 v[24:27], v[160:163], v[184:187], v[24:27]
	v_mfma_f32_16x16x32_bf16 v[16:19], v[152:155], v[192:195], v[16:19]
	v_mfma_f32_16x16x32_bf16 v[8:11], v[160:163], v[192:195], v[8:11]
	s_barrier
	s_add_u32 s2, s12, 0xb0000
	s_addc_u32 s3, s13, 0
	s_add_i32 s40, s31, s22
	v_lshl_add_u64 v[140:141], s[2:3], 0, v[128:129]
	s_mov_b32 m0, s40
	s_nop 0
	global_load_lds_dwordx4 v[140:141], off
	v_lshl_add_u64 v[140:141], s[2:3], 0, v[130:131]
	s_add_i32 m0, s40, 0x2000
	s_nop 0
	global_load_lds_dwordx4 v[140:141], off
	s_waitcnt vmcnt(6)
	s_barrier
	v_mfma_f32_16x16x32_bf16 v[44:47], v[196:199], v[164:167], 0
	v_mfma_f32_16x16x32_bf16 v[40:43], v[204:207], v[164:167], 0
	v_mfma_f32_16x16x32_bf16 v[36:39], v[196:199], v[172:175], 0
	v_mfma_f32_16x16x32_bf16 v[32:35], v[204:207], v[172:175], 0
	v_mfma_f32_16x16x32_bf16 v[20:23], v[196:199], v[180:183], 0
	v_mfma_f32_16x16x32_bf16 v[12:15], v[204:207], v[180:183], 0
	v_mfma_f32_16x16x32_bf16 v[4:7], v[196:199], v[188:191], 0
	v_mfma_f32_16x16x32_bf16 v[0:3], v[204:207], v[188:191], 0
	v_mfma_f32_16x16x32_bf16 v[44:47], v[200:203], v[168:171], v[44:47]
	v_mfma_f32_16x16x32_bf16 v[40:43], v[208:211], v[168:171], v[40:43]
	v_mfma_f32_16x16x32_bf16 v[36:39], v[200:203], v[176:179], v[36:39]
	v_mfma_f32_16x16x32_bf16 v[32:35], v[208:211], v[176:179], v[32:35]
	v_mfma_f32_16x16x32_bf16 v[20:23], v[200:203], v[184:187], v[20:23]
	v_mfma_f32_16x16x32_bf16 v[12:15], v[208:211], v[184:187], v[12:15]
	v_mfma_f32_16x16x32_bf16 v[4:7], v[200:203], v[192:195], v[4:7]
	v_mfma_f32_16x16x32_bf16 v[0:3], v[208:211], v[192:195], v[0:3]
	s_add_i32 s40, 0, 0x18000
	v_add_u32_e32 v160, s40, v147
	s_barrier
	ds_read_b128 v[140:143], v160
	ds_read_b128 v[152:155], v160 offset:1024
	ds_read_b128 v[156:159], v160 offset:2048
	ds_read_b128 v[160:163], v160 offset:3072
	s_add_u32 s2, s14, 0xb0000
	s_addc_u32 s3, s15, 0
	s_mov_b32 m0, s25
	v_lshl_add_u64 v[196:197], s[2:3], 0, v[128:129]
	ds_read_b128 v[164:167], v150 offset:32768
	ds_read_b128 v[168:171], v150 offset:33792
	ds_read_b128 v[172:175], v150 offset:34816
	ds_read_b128 v[176:179], v150 offset:35840
	ds_read_b128 v[180:183], v150 offset:36864
	ds_read_b128 v[184:187], v150 offset:37888
	ds_read_b128 v[188:191], v150 offset:38912
	ds_read_b128 v[192:195], v150 offset:39936
	global_load_lds_dwordx4 v[196:197], off
	v_lshl_add_u64 v[196:197], s[2:3], 0, v[130:131]
	s_mov_b32 m0, s26
	s_nop 0
	global_load_lds_dwordx4 v[196:197], off
	s_waitcnt lgkmcnt(8)
	s_barrier
	s_waitcnt lgkmcnt(0)
	s_waitcnt lgkmcnt(0)
	v_mfma_f32_16x16x32_bf16 v[124:127], v[140:143], v[164:167], v[124:127]
	v_mfma_f32_16x16x32_bf16 v[120:123], v[156:159], v[164:167], v[120:123]
	v_mfma_f32_16x16x32_bf16 v[116:119], v[140:143], v[172:175], v[116:119]
	v_mfma_f32_16x16x32_bf16 v[112:115], v[156:159], v[172:175], v[112:115]
	v_mfma_f32_16x16x32_bf16 v[92:95], v[140:143], v[180:183], v[92:95]
	v_mfma_f32_16x16x32_bf16 v[88:91], v[156:159], v[180:183], v[88:91]
	v_mfma_f32_16x16x32_bf16 v[84:87], v[140:143], v[188:191], v[84:87]
	v_mfma_f32_16x16x32_bf16 v[80:83], v[156:159], v[188:191], v[80:83]
	v_mfma_f32_16x16x32_bf16 v[124:127], v[152:155], v[168:171], v[124:127]
	v_mfma_f32_16x16x32_bf16 v[120:123], v[160:163], v[168:171], v[120:123]
	v_mfma_f32_16x16x32_bf16 v[116:119], v[152:155], v[176:179], v[116:119]
	v_mfma_f32_16x16x32_bf16 v[112:115], v[160:163], v[176:179], v[112:115]
	v_mfma_f32_16x16x32_bf16 v[92:95], v[152:155], v[184:187], v[92:95]
	v_mfma_f32_16x16x32_bf16 v[88:91], v[160:163], v[184:187], v[88:91]
	v_mfma_f32_16x16x32_bf16 v[84:87], v[152:155], v[192:195], v[84:87]
	v_mfma_f32_16x16x32_bf16 v[80:83], v[160:163], v[192:195], v[80:83]
	s_barrier
	s_add_i32 s14, 0, 0x1c000
	s_add_i32 s2, s40, s22
	v_add_u32_e32 v208, s14, v147
	v_lshl_add_u64 v[144:145], v[144:145], 0, s[8:9]
	s_mov_b32 m0, s2
	ds_read_b128 v[196:199], v208
	ds_read_b128 v[200:203], v208 offset:1024
	ds_read_b128 v[204:207], v208 offset:2048
	ds_read_b128 v[208:211], v208 offset:3072
	global_load_lds_dwordx4 v[144:145], off
	v_lshl_add_u64 v[144:145], v[212:213], 0, s[8:9]
	s_add_i32 m0, s2, 0x2000
	s_nop 0
	global_load_lds_dwordx4 v[144:145], off
	s_barrier
	s_waitcnt lgkmcnt(0)
	s_waitcnt lgkmcnt(0)
	v_mfma_f32_16x16x32_bf16 v[108:111], v[196:199], v[164:167], v[108:111]
	v_mfma_f32_16x16x32_bf16 v[104:107], v[204:207], v[164:167], v[104:107]
	v_mfma_f32_16x16x32_bf16 v[100:103], v[196:199], v[172:175], v[100:103]
	v_mfma_f32_16x16x32_bf16 v[96:99], v[204:207], v[172:175], v[96:99]
	v_mfma_f32_16x16x32_bf16 v[76:79], v[196:199], v[180:183], v[76:79]
	v_mfma_f32_16x16x32_bf16 v[72:75], v[204:207], v[180:183], v[72:75]
	v_mfma_f32_16x16x32_bf16 v[68:71], v[196:199], v[188:191], v[68:71]
	v_mfma_f32_16x16x32_bf16 v[64:67], v[204:207], v[188:191], v[64:67]
	v_mfma_f32_16x16x32_bf16 v[108:111], v[200:203], v[168:171], v[108:111]
	v_mfma_f32_16x16x32_bf16 v[104:107], v[208:211], v[168:171], v[104:107]
	v_mfma_f32_16x16x32_bf16 v[100:103], v[200:203], v[176:179], v[100:103]
	v_mfma_f32_16x16x32_bf16 v[96:99], v[208:211], v[176:179], v[96:99]
	v_mfma_f32_16x16x32_bf16 v[76:79], v[200:203], v[184:187], v[76:79]
	v_mfma_f32_16x16x32_bf16 v[72:75], v[208:211], v[184:187], v[72:75]
	v_mfma_f32_16x16x32_bf16 v[68:71], v[200:203], v[192:195], v[68:71]
	v_mfma_f32_16x16x32_bf16 v[64:67], v[208:211], v[192:195], v[64:67]
	s_mov_b32 m0, s28
	v_lshl_add_u64 v[144:145], v[214:215], 0, s[8:9]
	s_barrier
	ds_read_b128 v[164:167], v150 offset:49152
	ds_read_b128 v[168:171], v150 offset:50176
	ds_read_b128 v[172:175], v150 offset:51200
	ds_read_b128 v[176:179], v150 offset:52224
	ds_read_b128 v[180:183], v150 offset:53248
	ds_read_b128 v[184:187], v150 offset:54272
	ds_read_b128 v[188:191], v150 offset:55296
	ds_read_b128 v[192:195], v150 offset:56320
	global_load_lds_dwordx4 v[144:145], off
	v_lshl_add_u64 v[144:145], v[216:217], 0, s[8:9]
	s_mov_b32 m0, s29
	s_nop 0
	global_load_lds_dwordx4 v[144:145], off
	s_barrier
	s_waitcnt lgkmcnt(0)
	s_waitcnt lgkmcnt(0)
	v_mfma_f32_16x16x32_bf16 v[60:63], v[140:143], v[164:167], v[60:63]
	v_mfma_f32_16x16x32_bf16 v[56:59], v[156:159], v[164:167], v[56:59]
	v_mfma_f32_16x16x32_bf16 v[52:55], v[140:143], v[172:175], v[52:55]
	v_mfma_f32_16x16x32_bf16 v[48:51], v[156:159], v[172:175], v[48:51]
	v_mfma_f32_16x16x32_bf16 v[28:31], v[140:143], v[180:183], v[28:31]
	v_mfma_f32_16x16x32_bf16 v[24:27], v[156:159], v[180:183], v[24:27]
	v_mfma_f32_16x16x32_bf16 v[16:19], v[140:143], v[188:191], v[16:19]
	v_mfma_f32_16x16x32_bf16 v[8:11], v[156:159], v[188:191], v[8:11]
	v_mfma_f32_16x16x32_bf16 v[60:63], v[152:155], v[168:171], v[60:63]
	v_mfma_f32_16x16x32_bf16 v[56:59], v[160:163], v[168:171], v[56:59]
	v_mfma_f32_16x16x32_bf16 v[52:55], v[152:155], v[176:179], v[52:55]
	v_mfma_f32_16x16x32_bf16 v[48:51], v[160:163], v[176:179], v[48:51]
	v_mfma_f32_16x16x32_bf16 v[28:31], v[152:155], v[184:187], v[28:31]
	v_mfma_f32_16x16x32_bf16 v[24:27], v[160:163], v[184:187], v[24:27]
	v_mfma_f32_16x16x32_bf16 v[16:19], v[152:155], v[192:195], v[16:19]
	v_mfma_f32_16x16x32_bf16 v[8:11], v[160:163], v[192:195], v[8:11]
	s_barrier
	s_add_u32 s2, s12, 0xb0080
	s_addc_u32 s3, s13, 0
	s_add_i32 s12, s14, s22
	v_lshl_add_u64 v[140:141], s[2:3], 0, v[128:129]
	s_mov_b32 m0, s12
	s_nop 0
	global_load_lds_dwordx4 v[140:141], off
	v_lshl_add_u64 v[140:141], s[2:3], 0, v[130:131]
	s_add_i32 m0, s12, 0x2000
	s_nop 0
	global_load_lds_dwordx4 v[140:141], off
	s_waitcnt vmcnt(6)
	s_barrier
	v_mfma_f32_16x16x32_bf16 v[44:47], v[196:199], v[164:167], v[44:47]
	v_mfma_f32_16x16x32_bf16 v[40:43], v[204:207], v[164:167], v[40:43]
	v_mfma_f32_16x16x32_bf16 v[36:39], v[196:199], v[172:175], v[36:39]
	v_mfma_f32_16x16x32_bf16 v[32:35], v[204:207], v[172:175], v[32:35]
	v_mfma_f32_16x16x32_bf16 v[20:23], v[196:199], v[180:183], v[20:23]
	v_mfma_f32_16x16x32_bf16 v[12:15], v[204:207], v[180:183], v[12:15]
	v_mfma_f32_16x16x32_bf16 v[4:7], v[196:199], v[188:191], v[4:7]
	v_mfma_f32_16x16x32_bf16 v[0:3], v[204:207], v[188:191], v[0:3]
	v_mfma_f32_16x16x32_bf16 v[44:47], v[200:203], v[168:171], v[44:47]
	v_mfma_f32_16x16x32_bf16 v[40:43], v[208:211], v[168:171], v[40:43]
	v_mfma_f32_16x16x32_bf16 v[36:39], v[200:203], v[176:179], v[36:39]
	v_mfma_f32_16x16x32_bf16 v[32:35], v[208:211], v[176:179], v[32:35]
	v_mfma_f32_16x16x32_bf16 v[20:23], v[200:203], v[184:187], v[20:23]
	v_mfma_f32_16x16x32_bf16 v[12:15], v[208:211], v[184:187], v[12:15]
	v_mfma_f32_16x16x32_bf16 v[4:7], v[200:203], v[192:195], v[4:7]
	v_mfma_f32_16x16x32_bf16 v[0:3], v[208:211], v[192:195], v[0:3]
	s_add_i32 s39, s39, 2
	s_add_u32 s37, s37, 0x100
	s_addc_u32 s38, s38, 0
	s_cmp_gt_u32 s39, 41
	s_mov_b64 s[2:3], s[10:11]
	s_barrier
